# retention out_unit: decay scalars requested together; K tile loads issued behind the Q tile loads
# speedup vs baseline: 1.0032x; 1.0032x over previous
; DI float logsig(float x) { return -log1pf(__expf(-x)); }
; DI void out_unit(const Inputs& in, int l, unsigned char* ws, int half, int u, LAS unsigned char* lds, int tid) {
;     ...
;     const int L = half ? 2048 : 4096, NC = L / 128, h = u & 3, sn = u >> 2, s = sn / NC, n = sn % NC, row0 = s * L + n * 128, pos0 = n * 128;
;     bf16_t* proj = (bf16_t*)(ws + WS_PROJ); const float* rtc = (const float*)(ws + WS_RTC); const float* rts = (const float*)(ws + WS_RTS);
;     const bf16_t* SS = (const bf16_t*)(ws + WS_KV + 32 * MiB);
;     const float lgf = logsig(in.ret_decay[l * 8 + h]), lgb = logsig(in.ret_decay[l * 8 + 4 + h]);
.LBB0_731:
	s_ashr_i32 s13, s26, 2
	s_abs_i32 s15, s13
	s_mul_hi_u32 s16, s15, s24
	s_mul_i32 s17, s16, s20
	s_sub_i32 s15, s15, s17
	s_and_b32 s27, s26, 3
	s_ashr_i32 s14, s26, 31
	s_add_i32 s17, s16, 1
	s_sub_i32 s28, s15, s20
	s_cmp_ge_u32 s15, s20
	s_cselect_b32 s16, s17, s16
	s_cselect_b32 s15, s28, s15
	s_add_i32 s17, s16, 1
	s_cmp_ge_u32 s15, s20
	s_cselect_b32 s15, s17, s16
	s_xor_b32 s15, s15, s14
	s_sub_i32 s14, s15, s14
	s_mul_i32 s15, s14, s20
	s_sub_i32 s13, s13, s15
	s_lshl_b32 s14, s14, s21
	s_lshl_b32 s13, s13, 7
	s_or_b32 s44, s27, s77
	s_add_i32 s14, s13, s14
	s_lshl_b64 s[16:17], s[44:45], 2
	s_waitcnt lgkmcnt(0)
	s_add_u32 s16, s4, s16
	v_mov_b32_e32 v66, v64
	s_addc_u32 s17, s5, s17
	global_load_dword v0, v177, s[16:17]
	global_load_dword v166, v177, s[16:17] offset:16
	v_ashrrev_i32_e32 v19, 6, v66
	s_movk_i32 s15, 0x1100
	v_lshlrev_b32_e32 v91, 3, v66
	v_and_b32_e32 v20, 56, v91
	v_lshlrev_b32_e32 v176, 1, v20
	v_or_b32_e32 v21, 64, v91
	v_and_b32_e32 v68, 15, v66
	v_and_b32_e32 v18, 63, v66
	v_or_b32_e32 v141, 16, v68
	v_or_b32_e32 v114, 32, v68
	v_or_b32_e32 v95, 48, v18
	v_or_b32_e32 v112, 64, v68
	v_or_b32_e32 v110, 0x50, v68
	v_or_b32_e32 v108, 0x60, v68
	v_or_b32_e32 v100, 0x70, v18
	v_mul_u32_u24_e32 v96, 0x88, v95
	v_mad_u32_u24 v97, v68, s1, v224
	v_mad_u32_u24 v98, v68, s1, v254
	v_mad_u32_u24 v99, v68, s1, v219
	v_mul_u32_u24_e32 v101, 0x88, v100
	s_waitcnt vmcnt(0)
	v_mul_f32_e32 v0, 0xbfb8aa3b, v0
	v_exp_f32_e32 v2, v0
	s_nop 0
	v_add_f32_e32 v3, 1.0, v2
	v_add_f32_e32 v0, -1.0, v3
	v_sub_f32_e32 v1, v0, v3
	v_add_f32_e32 v1, 1.0, v1
	v_sub_f32_e32 v0, v2, v0
	v_add_f32_e32 v4, v0, v1
	v_frexp_mant_f32_e32 v0, v3
	v_cmp_gt_f32_e32 vcc, s31, v0
	v_cvt_f64_f32_e32 v[0:1], v3
	v_frexp_exp_i32_f64_e32 v0, v[0:1]
	v_subbrev_co_u32_e32 v0, vcc, 0, v0, vcc
	v_sub_u32_e32 v1, 0, v0
	v_ldexp_f32 v3, v3, v1
	v_ldexp_f32 v1, v4, v1
	v_add_f32_e32 v4, -1.0, v3
	v_add_f32_e32 v5, 1.0, v4
	v_sub_f32_e32 v5, v3, v5
	v_add_f32_e32 v5, v1, v5
	v_add_f32_e32 v6, v4, v5
	v_sub_f32_e32 v4, v6, v4
	v_sub_f32_e32 v4, v5, v4
	v_add_f32_e32 v5, 1.0, v3
	v_add_f32_e32 v7, -1.0, v5
	v_sub_f32_e32 v3, v3, v7
	v_add_f32_e32 v1, v1, v3
	v_add_f32_e32 v3, v5, v1
	v_sub_f32_e32 v5, v3, v5
	v_sub_f32_e32 v1, v1, v5
	v_rcp_f32_e32 v5, v3
	v_cvt_f32_i32_e32 v0, v0
	v_cmp_neq_f32_e32 vcc, s34, v2
	v_mul_f32_e32 v7, v6, v5
	v_mul_f32_e32 v8, v3, v7
	v_fma_f32 v9, v7, v3, -v8
	v_fmac_f32_e32 v9, v7, v1
	v_add_f32_e32 v10, v8, v9
	v_sub_f32_e32 v11, v6, v10
	v_sub_f32_e32 v6, v6, v11
	v_sub_f32_e32 v8, v10, v8
	v_sub_f32_e32 v6, v6, v10
	v_add_f32_e32 v4, v4, v6
	v_sub_f32_e32 v6, v8, v9
	v_add_f32_e32 v4, v6, v4
	v_add_f32_e32 v6, v11, v4
	v_mul_f32_e32 v8, v5, v6
	v_mul_f32_e32 v9, v3, v8
	v_fma_f32 v3, v8, v3, -v9
	v_fmac_f32_e32 v3, v8, v1
	v_sub_f32_e32 v1, v11, v6
	v_add_f32_e32 v1, v4, v1
	v_add_f32_e32 v4, v9, v3
	v_sub_f32_e32 v10, v6, v4
	v_sub_f32_e32 v6, v6, v10
	v_sub_f32_e32 v9, v4, v9
	v_sub_f32_e32 v4, v6, v4
	v_add_f32_e32 v1, v1, v4
	v_sub_f32_e32 v3, v9, v3
	v_add_f32_e32 v1, v3, v1
	v_add_f32_e32 v3, v7, v8
	v_add_f32_e32 v1, v10, v1
	v_sub_f32_e32 v4, v3, v7
	v_mul_f32_e32 v1, v5, v1
	v_sub_f32_e32 v4, v8, v4
	v_add_f32_e32 v1, v4, v1
	v_mul_f32_e32 v7, 0x3f317218, v0
	v_add_f32_e32 v4, v3, v1
	v_fma_f32 v8, v0, s33, -v7
	v_mul_f32_e32 v5, v4, v4
	v_fmac_f32_e32 v8, 0xb102e308, v0
	v_sub_f32_e32 v0, v4, v3
	v_fmamk_f32 v6, v5, 0x3e9b6dac, v218
	v_sub_f32_e32 v0, v1, v0
	v_add_f32_e32 v1, v7, v8
	v_fmaak_f32 v6, v5, v6, 0x3f2aaada
	v_sub_f32_e32 v3, v1, v7
	v_ldexp_f32 v7, v4, 1
	v_mul_f32_e32 v4, v4, v5
	v_mul_f32_e32 v4, v4, v6
	v_add_f32_e32 v5, v7, v4
	v_sub_f32_e32 v6, v5, v7
	v_ldexp_f32 v0, v0, 1
	v_sub_f32_e32 v4, v4, v6
	v_add_f32_e32 v0, v0, v4
	v_add_f32_e32 v4, v5, v0
	v_sub_f32_e32 v5, v4, v5
	v_sub_f32_e32 v0, v0, v5
	v_add_f32_e32 v5, v1, v4
	v_sub_f32_e32 v6, v5, v1
	v_sub_f32_e32 v7, v5, v6
	v_sub_f32_e32 v3, v8, v3
	v_sub_f32_e32 v1, v1, v7
	v_sub_f32_e32 v4, v4, v6
	v_add_f32_e32 v1, v4, v1
	v_add_f32_e32 v4, v3, v0
	v_sub_f32_e32 v6, v4, v3
	v_sub_f32_e32 v7, v4, v6
	v_sub_f32_e32 v3, v3, v7
	v_sub_f32_e32 v0, v0, v6
	v_add_f32_e32 v1, v4, v1
	v_add_f32_e32 v0, v0, v3
	v_add_f32_e32 v3, v5, v1
	v_sub_f32_e32 v4, v3, v5
	v_sub_f32_e32 v1, v1, v4
	v_add_f32_e32 v0, v0, v1
	v_add_f32_e32 v0, v3, v0
	v_cndmask_b32_e32 v0, v221, v0, vcc
	v_cmp_ngt_f32_e32 vcc, -1.0, v2
	s_nop 1
	v_cndmask_b32_e32 v0, v222, v0, vcc
	v_cmp_neq_f32_e32 vcc, -1.0, v2
	s_nop 1
	v_cndmask_b32_e32 v0, v223, v0, vcc
	v_cmp_lt_f32_e64 vcc, |v2|, s35
	s_nop 1
	v_cndmask_b32_e32 v60, v0, v2, vcc
	v_mov_b32_e32 v0, v166
	s_waitcnt vmcnt(0)
; #define LAS __attribute__((address_space(3)))
; DI float logsig(float x) { return -log1pf(__expf(-x)); }
; DI void out_unit(const Inputs& in, int l, unsigned char* ws, int half, int u, LAS unsigned char* lds, int tid) {
;     ...
;     const float lgf = logsig(in.ret_decay[l * 8 + h]), lgb = logsig(in.ret_decay[l * 8 + 4 + h]);
;     const int wave = tid >> 6, lane = tid & 63, l15 = lane & 15, quad = lane >> 4;
;     LAS unsigned char* Qt = lds; LAS unsigned char* Kt = lds + TILE_B; LAS unsigned char* VTt = lds + 2 * TILE_B; LAS unsigned char* Ps = lds + 3 * TILE_B + wave * (16 * TS * 2);
;     stage_rot_rm_b(Qt, proj + (size_t)row0 * PC + C_RQ + 128 * h, rtc, rts, pos0, 1.0f, tid);
;     stage_rot_rm_b(Kt, proj + (size_t)row0 * PC + C_RK + 128 * h, rtc, rts, pos0, 0.088388347648318440f, tid);
	v_mul_f32_e32 v0, 0xbfb8aa3b, v0
	v_exp_f32_e32 v2, v0
	s_nop 0
	v_add_f32_e32 v3, 1.0, v2
	v_add_f32_e32 v0, -1.0, v3
	v_sub_f32_e32 v1, v0, v3
	v_add_f32_e32 v1, 1.0, v1
	v_sub_f32_e32 v0, v2, v0
	v_add_f32_e32 v4, v0, v1
	v_frexp_mant_f32_e32 v0, v3
	v_cmp_gt_f32_e32 vcc, s31, v0
	v_cvt_f64_f32_e32 v[0:1], v3
	v_frexp_exp_i32_f64_e32 v0, v[0:1]
	v_subbrev_co_u32_e32 v0, vcc, 0, v0, vcc
	v_sub_u32_e32 v1, 0, v0
	v_ldexp_f32 v3, v3, v1
	v_ldexp_f32 v1, v4, v1
	v_add_f32_e32 v4, -1.0, v3
	v_add_f32_e32 v5, 1.0, v4
	v_sub_f32_e32 v5, v3, v5
	v_add_f32_e32 v5, v1, v5
	v_add_f32_e32 v6, v4, v5
	v_sub_f32_e32 v4, v6, v4
	v_sub_f32_e32 v4, v5, v4
	v_add_f32_e32 v5, 1.0, v3
	v_add_f32_e32 v7, -1.0, v5
	v_sub_f32_e32 v3, v3, v7
	v_add_f32_e32 v1, v1, v3
	v_add_f32_e32 v3, v5, v1
	v_sub_f32_e32 v5, v3, v5
	v_sub_f32_e32 v1, v1, v5
	v_rcp_f32_e32 v5, v3
	v_cvt_f32_i32_e32 v0, v0
	v_cmp_neq_f32_e32 vcc, s34, v2
	v_mul_f32_e32 v7, v6, v5
	v_mul_f32_e32 v8, v3, v7
	v_fma_f32 v9, v7, v3, -v8
	v_fmac_f32_e32 v9, v7, v1
	v_add_f32_e32 v10, v8, v9
	v_sub_f32_e32 v11, v6, v10
	v_sub_f32_e32 v6, v6, v11
	v_sub_f32_e32 v8, v10, v8
	v_sub_f32_e32 v6, v6, v10
	v_add_f32_e32 v4, v4, v6
	v_sub_f32_e32 v6, v8, v9
	v_add_f32_e32 v4, v6, v4
	v_add_f32_e32 v6, v11, v4
	v_mul_f32_e32 v8, v5, v6
	v_mul_f32_e32 v9, v3, v8
	v_fma_f32 v3, v8, v3, -v9
	v_fmac_f32_e32 v3, v8, v1
	v_sub_f32_e32 v1, v11, v6
	v_add_f32_e32 v1, v4, v1
	v_add_f32_e32 v4, v9, v3
	v_sub_f32_e32 v10, v6, v4
	v_sub_f32_e32 v6, v6, v10
	v_sub_f32_e32 v9, v4, v9
	v_sub_f32_e32 v4, v6, v4
	v_add_f32_e32 v1, v1, v4
	v_sub_f32_e32 v3, v9, v3
	v_add_f32_e32 v1, v3, v1
	v_add_f32_e32 v3, v7, v8
	v_add_f32_e32 v1, v10, v1
	v_sub_f32_e32 v4, v3, v7
	v_mul_f32_e32 v1, v5, v1
	v_sub_f32_e32 v4, v8, v4
	v_add_f32_e32 v1, v4, v1
	v_mul_f32_e32 v7, 0x3f317218, v0
	v_add_f32_e32 v4, v3, v1
	v_fma_f32 v8, v0, s33, -v7
	v_mul_f32_e32 v5, v4, v4
	v_fmac_f32_e32 v8, 0xb102e308, v0
	v_sub_f32_e32 v0, v4, v3
	v_fmamk_f32 v6, v5, 0x3e9b6dac, v218
	v_sub_f32_e32 v0, v1, v0
	v_add_f32_e32 v1, v7, v8
	v_fmaak_f32 v6, v5, v6, 0x3f2aaada
	v_sub_f32_e32 v3, v1, v7
	v_ldexp_f32 v7, v4, 1
	v_mul_f32_e32 v4, v4, v5
	v_mul_f32_e32 v4, v4, v6
	v_add_f32_e32 v5, v7, v4
	v_sub_f32_e32 v6, v5, v7
	v_ldexp_f32 v0, v0, 1
	v_sub_f32_e32 v4, v4, v6
	v_add_f32_e32 v0, v0, v4
	v_add_f32_e32 v4, v5, v0
	v_sub_f32_e32 v5, v4, v5
	v_sub_f32_e32 v0, v0, v5
	v_add_f32_e32 v5, v1, v4
	v_sub_f32_e32 v6, v5, v1
	v_sub_f32_e32 v7, v5, v6
	v_sub_f32_e32 v3, v8, v3
	v_sub_f32_e32 v1, v1, v7
	v_sub_f32_e32 v4, v4, v6
	v_add_f32_e32 v1, v4, v1
	v_add_f32_e32 v4, v3, v0
	v_sub_f32_e32 v6, v4, v3
	v_sub_f32_e32 v7, v4, v6
	v_sub_f32_e32 v3, v3, v7
	v_sub_f32_e32 v0, v0, v6
	v_add_f32_e32 v1, v4, v1
	v_add_f32_e32 v0, v0, v3
	v_add_f32_e32 v3, v5, v1
	v_sub_f32_e32 v4, v3, v5
	v_sub_f32_e32 v1, v1, v4
	v_add_f32_e32 v0, v0, v1
	v_add_f32_e32 v0, v3, v0
	v_cndmask_b32_e32 v0, v221, v0, vcc
	v_cmp_ngt_f32_e32 vcc, -1.0, v2
	v_ashrrev_i32_e32 v10, 3, v66
	v_ashrrev_i32_e32 v11, 31, v10
	v_cndmask_b32_e32 v0, v222, v0, vcc
	v_cmp_neq_f32_e32 vcc, -1.0, v2
	v_add_u32_e32 v12, s13, v10
	v_lshlrev_b64 v[8:9], 14, v[10:11]
	v_cndmask_b32_e32 v0, v223, v0, vcc
	v_cmp_lt_f32_e64 vcc, |v2|, s35
	v_ashrrev_i32_e32 v13, 31, v12
	v_lshlrev_b64 v[14:15], 8, v[12:13]
	v_cndmask_b32_e32 v67, v0, v2, vcc
	v_mul_lo_u32 v0, v19, s15
	s_ashr_i32 s15, s14, 31
	s_lshl_b64 s[16:17], s[14:15], 14
	s_add_u32 s15, s6, s16
	s_addc_u32 s17, s7, s17
	s_lshl_b32 s44, s27, 8
	s_add_u32 s16, s15, s44
	s_addc_u32 s17, s17, 0
	v_add_u32_e32 v65, s42, v0
	v_lshl_add_u64 v[0:1], s[16:17], 0, v[8:9]
	v_lshl_add_u64 v[0:1], v[0:1], 0, v[176:177]
	v_lshl_add_u64 v[16:17], s[8:9], 0, v[14:15]
	v_lshlrev_b32_e32 v12, 2, v20
	v_mov_b32_e32 v13, v177
	v_lshl_add_u64 v[14:15], s[10:11], 0, v[14:15]
	global_load_dwordx4 v[4:7], v[0:1], off offset:3072
	s_nop 0
	global_load_dwordx4 v[0:3], v[0:1], off offset:3200
	v_lshl_add_u64 v[22:23], v[16:17], 0, v[12:13]
	v_lshl_add_u64 v[30:31], v[14:15], 0, v[12:13]
	global_load_dwordx4 v[14:17], v[22:23], off offset:16
	s_nop 0
	global_load_dwordx4 v[22:25], v[22:23], off
	s_nop 0
	global_load_dwordx4 v[26:29], v[30:31], off offset:16
	s_nop 0
	global_load_dwordx4 v[30:33], v[30:31], off
	v_add_u32_e32 v58, 64, v10
	v_ashrrev_i32_e32 v59, 31, v58
	v_add_u32_e32 v42, s13, v58
	v_lshlrev_b64 v[62:63], 14, v[58:59]
	v_ashrrev_i32_e32 v43, 31, v42
	v_lshl_add_u64 v[34:35], s[16:17], 0, v[62:63]
	v_lshlrev_b64 v[42:43], 8, v[42:43]
	v_lshl_add_u64 v[38:39], v[34:35], 0, v[176:177]
	v_lshl_add_u64 v[44:45], s[8:9], 0, v[42:43]
	global_load_dwordx4 v[34:37], v[38:39], off offset:3072
	s_nop 0
	global_load_dwordx4 v[38:41], v[38:39], off offset:3200
	v_lshl_add_u64 v[46:47], v[44:45], 0, v[12:13]
	v_lshl_add_u64 v[42:43], s[10:11], 0, v[42:43]
	v_lshl_add_u64 v[12:13], v[42:43], 0, v[12:13]
	global_load_dwordx4 v[42:45], v[46:47], off offset:16
	s_nop 0
	global_load_dwordx4 v[46:49], v[46:47], off
	s_nop 0
	global_load_dwordx4 v[50:53], v[12:13], off offset:16
	global_load_dwordx4 v[54:57], v[12:13], off
	v_mul_lo_u32 v59, v10, s1
	v_and_b32_e32 v11, 0x78, v10
	v_xad_u32 v11, v11, v20, v59
	v_lshl_add_u32 v61, v11, 1, 0
	s_add_u32 s28, s16, 0x1000
	s_addc_u32 s29, s17, 0
	v_lshl_add_u64 v[168:169], s[28:29], 0, v[8:9]
	v_lshl_add_u64 v[168:169], v[168:169], 0, v[176:177]
	global_load_dwordx4 v[170:173], v[168:169], off
	global_load_dwordx4 v[178:181], v[168:169], off offset:128
	v_lshl_add_u64 v[168:169], s[28:29], 0, v[62:63]
	v_lshl_add_u64 v[168:169], v[168:169], 0, v[176:177]
	global_load_dwordx4 v[182:185], v[168:169], off
	global_load_dwordx4 v[186:189], v[168:169], off offset:128
	s_movk_i32 s13, 0x60
	s_waitcnt vmcnt(15)
; #define LAS __attribute__((address_space(3)))
; DI unsigned cvt_pk_bf16(float lo, float hi) { const f32x2 v = {lo, hi}; return __builtin_bit_cast(unsigned, __builtin_convertvector(v, bf16x2_t)); }
; DI void unpack8(const u32x4 w, float (&f)[8]) { f[0] = bflo(w.x); f[1] = bfhi(w.x); f[2] = bflo(w.y); f[3] = bfhi(w.y); f[4] = bflo(w.z); f[5] = bfhi(w.z); f[6] = bflo(w.w); f[7] = bfhi(w.w); }
; DI void rot_apply(const RotIn& r, float (&o1)[8], float (&o2)[8]) {
;     float x1[8], x2[8]; unpack8(r.a, x1); unpack8(r.b, x2);
; #pragma unroll
;     for (int e = 0; e < 8; ++e) { const float c = e < 4 ? r.ca[e & 3] : r.cb[e & 3], s = e < 4 ? r.sa[e & 3] : r.sb[e & 3]; o1[e] = x1[e] * c - x2[e] * s; o2[e] = x1[e] * s + x2[e] * c; }
; }
; DI void stage_rot_rm_b(LAS unsigned char* dst, const bf16_t* src, const float* rtc, const float* rts, int pos0, float scale, int tid) {
;     const RotIn r0 = rot_load(src, rtc, rts, pos0, tid >> 3, (tid & 7) * 8), r1 = rot_load(src, rtc, rts, pos0, 64 + (tid >> 3), (tid & 7) * 8);
; #pragma unroll
;     for (int k = 0; k < 2; ++k) { const int j = 64 * k + (tid >> 3), d0 = (tid & 7) * 8; float o1[8], o2[8]; rot_apply(k ? r1 : r0, o1, o2);
;         u32x4 w1, w2; w1.x = cvt_pk_bf16(o1[0] * scale, o1[1] * scale); w1.y = cvt_pk_bf16(o1[2] * scale, o1[3] * scale); w1.z = cvt_pk_bf16(o1[4] * scale, o1[5] * scale); w1.w = cvt_pk_bf16(o1[6] * scale, o1[7] * scale);
;         w2.x = cvt_pk_bf16(o2[0] * scale, o2[1] * scale); w2.y = cvt_pk_bf16(o2[2] * scale, o2[3] * scale); w2.z = cvt_pk_bf16(o2[4] * scale, o2[5] * scale); w2.w = cvt_pk_bf16(o2[6] * scale, o2[7] * scale);
;         *(LAS u32x4*)(dst + sw(j, d0) * 2) = w1; *(LAS u32x4*)(dst + sw(j, 64 + d0) * 2) = w2; }
	v_lshlrev_b32_e32 v12, 16, v4
	s_waitcnt vmcnt(14)
	v_lshlrev_b32_e32 v70, 16, v0
	v_and_b32_e32 v71, 0xffff0000, v0
	v_and_b32_e32 v13, 0xffff0000, v4
	s_waitcnt vmcnt(10)
	v_pk_mul_f32 v[72:73], v[30:31], v[70:71]
	v_lshlrev_b32_e32 v0, 16, v1
	v_pk_fma_f32 v[72:73], v[22:23], v[12:13], v[72:73] neg_lo:[0,0,1] neg_hi:[0,0,1]
	v_pk_mul_f32 v[12:13], v[30:31], v[12:13]
	v_and_b32_e32 v1, 0xffff0000, v1
	v_pk_fma_f32 v[12:13], v[22:23], v[70:71], v[12:13]
	v_lshlrev_b32_e32 v4, 16, v5
	v_and_b32_e32 v5, 0xffff0000, v5
	v_pk_mul_f32 v[70:71], v[32:33], v[0:1]
	s_nop 0
	v_pk_fma_f32 v[70:71], v[24:25], v[4:5], v[70:71] neg_lo:[0,0,1] neg_hi:[0,0,1]
	v_pk_mul_f32 v[4:5], v[32:33], v[4:5]
	s_nop 0
	v_pk_fma_f32 v[74:75], v[24:25], v[0:1], v[4:5]
	v_lshlrev_b32_e32 v4, 16, v2
	v_and_b32_e32 v5, 0xffff0000, v2
	v_lshlrev_b32_e32 v0, 16, v6
	v_and_b32_e32 v1, 0xffff0000, v6
	v_pk_mul_f32 v[76:77], v[26:27], v[4:5]
	v_lshlrev_b32_e32 v2, 16, v3
	v_pk_fma_f32 v[76:77], v[14:15], v[0:1], v[76:77] neg_lo:[0,0,1] neg_hi:[0,0,1]
	v_pk_mul_f32 v[0:1], v[26:27], v[0:1]
	v_and_b32_e32 v3, 0xffff0000, v3
	v_pk_fma_f32 v[78:79], v[14:15], v[4:5], v[0:1]
	v_lshlrev_b32_e32 v0, 16, v7
	v_and_b32_e32 v1, 0xffff0000, v7
	v_pk_mul_f32 v[4:5], v[28:29], v[2:3]
	v_cvt_pk_bf16_f32 v6, v78, v79
	v_pk_fma_f32 v[4:5], v[16:17], v[0:1], v[4:5] neg_lo:[0,0,1] neg_hi:[0,0,1]
	v_pk_mul_f32 v[0:1], v[28:29], v[0:1]
	s_nop 0
	v_pk_fma_f32 v[80:81], v[16:17], v[2:3], v[0:1]
	v_cvt_pk_bf16_f32 v0, v72, v73
	v_cvt_pk_bf16_f32 v1, v70, v71
	v_cvt_pk_bf16_f32 v2, v76, v77
	v_cvt_pk_bf16_f32 v3, v4, v5
	ds_write_b128 v61, v[0:3]
	v_bitop3_b32 v0, v21, s0, v10 bitop3:0x48
	v_add_u32_e32 v0, v0, v59
	v_cvt_pk_bf16_f32 v4, v12, v13
	v_cvt_pk_bf16_f32 v5, v74, v75
	v_cvt_pk_bf16_f32 v7, v80, v81
	v_lshl_add_u32 v69, v0, 1, 0
	s_waitcnt vmcnt(8)
	v_lshlrev_b32_e32 v2, 16, v38
	v_and_b32_e32 v3, 0xffff0000, v38
	ds_write_b128 v69, v[4:7]
	v_lshlrev_b32_e32 v0, 16, v34
	v_and_b32_e32 v1, 0xffff0000, v34
	s_waitcnt vmcnt(4)
	v_pk_mul_f32 v[4:5], v[54:55], v[2:3]
	s_nop 0
	v_pk_fma_f32 v[4:5], v[46:47], v[0:1], v[4:5] neg_lo:[0,0,1] neg_hi:[0,0,1]
	v_pk_mul_f32 v[0:1], v[54:55], v[0:1]
	s_nop 0
	v_pk_fma_f32 v[6:7], v[46:47], v[2:3], v[0:1]
	v_lshlrev_b32_e32 v2, 16, v39
	v_and_b32_e32 v3, 0xffff0000, v39
	v_lshlrev_b32_e32 v0, 16, v35
	v_and_b32_e32 v1, 0xffff0000, v35
	v_pk_mul_f32 v[10:11], v[56:57], v[2:3]
	s_nop 0
	v_pk_fma_f32 v[10:11], v[48:49], v[0:1], v[10:11] neg_lo:[0,0,1] neg_hi:[0,0,1]
	v_pk_mul_f32 v[0:1], v[56:57], v[0:1]
	s_nop 0
	v_pk_fma_f32 v[12:13], v[48:49], v[2:3], v[0:1]
	v_lshlrev_b32_e32 v2, 16, v40
	v_and_b32_e32 v3, 0xffff0000, v40
	v_lshlrev_b32_e32 v0, 16, v36
	v_and_b32_e32 v1, 0xffff0000, v36
	v_pk_mul_f32 v[34:35], v[50:51], v[2:3]
	s_nop 0
	v_pk_fma_f32 v[34:35], v[42:43], v[0:1], v[34:35] neg_lo:[0,0,1] neg_hi:[0,0,1]
	v_pk_mul_f32 v[0:1], v[50:51], v[0:1]
	s_nop 0
	v_pk_fma_f32 v[38:39], v[42:43], v[2:3], v[0:1]
	v_lshlrev_b32_e32 v2, 16, v41
	v_and_b32_e32 v3, 0xffff0000, v41
	v_lshlrev_b32_e32 v0, 16, v37
	v_and_b32_e32 v1, 0xffff0000, v37
	v_pk_mul_f32 v[36:37], v[52:53], v[2:3]
	s_nop 0
	v_pk_fma_f32 v[36:37], v[44:45], v[0:1], v[36:37] neg_lo:[0,0,1] neg_hi:[0,0,1]
	v_pk_mul_f32 v[0:1], v[52:53], v[0:1]
	s_nop 0
	v_pk_fma_f32 v[40:41], v[44:45], v[2:3], v[0:1]
	v_cvt_pk_bf16_f32 v1, v10, v11
	v_add_u32_e32 v10, 0x2200, v59
	v_and_b32_e32 v11, 0x78, v58
	v_xad_u32 v11, v11, v20, v10
	v_cvt_pk_bf16_f32 v0, v4, v5
	v_cvt_pk_bf16_f32 v2, v34, v35
	v_cvt_pk_bf16_f32 v3, v36, v37
	v_cvt_pk_bf16_f32 v4, v6, v7
	v_cvt_pk_bf16_f32 v7, v40, v41
	v_lshl_add_u32 v40, v11, 1, 0
	ds_write_b128 v40, v[0:3]
	v_bitop3_b32 v0, v58, s0, v21 bitop3:0x48
	v_add_u32_e32 v0, v0, v10
	v_cvt_pk_bf16_f32 v5, v12, v13
	v_cvt_pk_bf16_f32 v6, v38, v39
	v_lshl_add_u32 v41, v0, 1, 0
	ds_write_b128 v41, v[4:7]
	s_nop 0
	v_ashrrev_i32_e32 v58, 4, v66
	v_ashrrev_i32_e32 v59, 31, v58
	v_bitop3_b32 v134, v58, s0, v91 bitop3:0x48
	s_waitcnt vmcnt(3)
	v_mov_b32_e32 v0, v170
	v_mov_b32_e32 v1, v171
	v_mov_b32_e32 v2, v172
	v_mov_b32_e32 v3, v173
	v_lshlrev_b32_e32 v12, 16, v0
	s_waitcnt vmcnt(2)
	v_mov_b32_e32 v4, v178
	v_mov_b32_e32 v5, v179
	v_mov_b32_e32 v6, v180
	v_mov_b32_e32 v7, v181
	v_lshlrev_b32_e32 v20, 16, v4
	v_and_b32_e32 v21, 0xffff0000, v4
	v_and_b32_e32 v13, 0xffff0000, v0
	v_pk_mul_f32 v[38:39], v[22:23], v[20:21]
	v_pk_mul_f32 v[20:21], v[30:31], v[20:21]
	v_pk_fma_f32 v[38:39], v[30:31], v[12:13], v[38:39]
	v_pk_fma_f32 v[12:13], v[22:23], v[12:13], v[20:21] neg_lo:[0,0,1] neg_hi:[0,0,1]
	v_lshlrev_b32_e32 v20, 16, v5
	v_pk_mul_f32 v[12:13], v[12:13], s[76:77] op_sel_hi:[1,0]
	v_and_b32_e32 v21, 0xffff0000, v5
	v_cvt_pk_bf16_f32 v0, v12, v13
	v_pk_mul_f32 v[12:13], v[38:39], s[76:77] op_sel_hi:[1,0]
	v_pk_mul_f32 v[22:23], v[24:25], v[20:21]
	v_cvt_pk_bf16_f32 v4, v12, v13
	v_lshlrev_b32_e32 v12, 16, v1
	v_and_b32_e32 v13, 0xffff0000, v1
	v_pk_mul_f32 v[20:21], v[32:33], v[20:21]
	v_pk_fma_f32 v[22:23], v[32:33], v[12:13], v[22:23]
	v_pk_fma_f32 v[12:13], v[24:25], v[12:13], v[20:21] neg_lo:[0,0,1] neg_hi:[0,0,1]
	v_lshlrev_b32_e32 v20, 16, v6
	v_pk_mul_f32 v[12:13], v[12:13], s[76:77] op_sel_hi:[1,0]
	v_and_b32_e32 v21, 0xffff0000, v6
	v_cvt_pk_bf16_f32 v1, v12, v13
	v_pk_mul_f32 v[12:13], v[22:23], s[76:77] op_sel_hi:[1,0]
	v_pk_mul_f32 v[22:23], v[14:15], v[20:21]
	v_cvt_pk_bf16_f32 v5, v12, v13
	v_lshlrev_b32_e32 v12, 16, v2
	v_and_b32_e32 v13, 0xffff0000, v2
	v_pk_mul_f32 v[20:21], v[26:27], v[20:21]
	v_pk_fma_f32 v[22:23], v[26:27], v[12:13], v[22:23]
	v_pk_fma_f32 v[12:13], v[14:15], v[12:13], v[20:21] neg_lo:[0,0,1] neg_hi:[0,0,1]
	v_lshlrev_b32_e32 v14, 16, v7
	v_pk_mul_f32 v[12:13], v[12:13], s[76:77] op_sel_hi:[1,0]
	v_and_b32_e32 v15, 0xffff0000, v7
	v_cvt_pk_bf16_f32 v2, v12, v13
	v_pk_mul_f32 v[12:13], v[22:23], s[76:77] op_sel_hi:[1,0]
	v_pk_mul_f32 v[20:21], v[16:17], v[14:15]
	v_cvt_pk_bf16_f32 v6, v12, v13
	v_lshlrev_b32_e32 v12, 16, v3
	v_and_b32_e32 v13, 0xffff0000, v3
	v_pk_mul_f32 v[14:15], v[28:29], v[14:15]
	v_pk_fma_f32 v[20:21], v[28:29], v[12:13], v[20:21]
	v_pk_fma_f32 v[12:13], v[16:17], v[12:13], v[14:15] neg_lo:[0,0,1] neg_hi:[0,0,1]
	v_mul_u32_u24_e32 v17, 0x88, v68
	v_pk_mul_f32 v[12:13], v[12:13], s[76:77] op_sel_hi:[1,0]
	s_nop 0
	v_cvt_pk_bf16_f32 v3, v12, v13
	v_pk_mul_f32 v[12:13], v[20:21], s[76:77] op_sel_hi:[1,0]
	v_mad_u32_u24 v20, v68, s1, v225
	v_cvt_pk_bf16_f32 v7, v12, v13
	ds_write_b128 v61, v[0:3] offset:34816
	ds_write_b128 v69, v[4:7] offset:34816
	s_waitcnt vmcnt(0)
; #define LAS __attribute__((address_space(3)))
; DI unsigned cvt_pk_bf16(float lo, float hi) { const f32x2 v = {lo, hi}; return __builtin_bit_cast(unsigned, __builtin_convertvector(v, bf16x2_t)); }
; DI void stage_rot_rm_b(LAS unsigned char* dst, const bf16_t* src, const float* rtc, const float* rts, int pos0, float scale, int tid) {
;     ...
;     for (int k = 0; k < 2; ++k) { const int j = 64 * k + (tid >> 3), d0 = (tid & 7) * 8; float o1[8], o2[8]; rot_apply(k ? r1 : r0, o1, o2);
;         u32x4 w1, w2; w1.x = cvt_pk_bf16(o1[0] * scale, o1[1] * scale); w1.y = cvt_pk_bf16(o1[2] * scale, o1[3] * scale); w1.z = cvt_pk_bf16(o1[4] * scale, o1[5] * scale); w1.w = cvt_pk_bf16(o1[6] * scale, o1[7] * scale);
;         w2.x = cvt_pk_bf16(o2[0] * scale, o2[1] * scale); w2.y = cvt_pk_bf16(o2[2] * scale, o2[3] * scale); w2.z = cvt_pk_bf16(o2[4] * scale, o2[5] * scale); w2.w = cvt_pk_bf16(o2[6] * scale, o2[7] * scale);
;         *(LAS u32x4*)(dst + sw(j, d0) * 2) = w1; *(LAS u32x4*)(dst + sw(j, 64 + d0) * 2) = w2; }
; DI void stage_T_b(LAS unsigned char* dst, const bf16_t* src, int tid) {
;     LAS bf16_t* T = (LAS bf16_t*)dst;
;     u32x4 wv[4];
; #pragma unroll
;     for (int k = 0; k < 4; ++k) { const int it = tid + 512 * k, j = it >> 4, c0 = (it & 15) * 8; wv[k] = *(const u32x4*)(src + (size_t)j * PC + c0); }
; #pragma unroll
;     for (int k = 0; k < 4; ++k) { const int it = tid + 512 * k, j = it >> 4, c0 = (it & 15) * 8; const u32x4 w = wv[k];
;         T[sw(c0 + 0, j)] = (bf16_t)(w.x & 0xffff); T[sw(c0 + 1, j)] = (bf16_t)(w.x >> 16); T[sw(c0 + 2, j)] = (bf16_t)(w.y & 0xffff); T[sw(c0 + 3, j)] = (bf16_t)(w.y >> 16);
;         T[sw(c0 + 4, j)] = (bf16_t)(w.z & 0xffff); T[sw(c0 + 5, j)] = (bf16_t)(w.z >> 16); T[sw(c0 + 6, j)] = (bf16_t)(w.w & 0xffff); T[sw(c0 + 7, j)] = (bf16_t)(w.w >> 16); }
; }
	v_mov_b32_e32 v8, v182
	v_mov_b32_e32 v9, v183
	v_mov_b32_e32 v10, v184
	v_mov_b32_e32 v11, v185
	v_mov_b32_e32 v34, v186
	v_mov_b32_e32 v35, v187
	v_mov_b32_e32 v36, v188
	v_mov_b32_e32 v37, v189
	v_lshlrev_b32_e32 v2, 16, v34
	v_and_b32_e32 v3, 0xffff0000, v34
	v_lshlrev_b32_e32 v0, 16, v8
	v_and_b32_e32 v1, 0xffff0000, v8
	v_pk_mul_f32 v[4:5], v[46:47], v[2:3]
	v_pk_mul_f32 v[2:3], v[54:55], v[2:3]
	v_pk_fma_f32 v[4:5], v[54:55], v[0:1], v[4:5]
	v_pk_fma_f32 v[0:1], v[46:47], v[0:1], v[2:3] neg_lo:[0,0,1] neg_hi:[0,0,1]
	v_pk_mul_f32 v[2:3], v[4:5], s[76:77] op_sel_hi:[1,0]
	v_lshlrev_b32_e32 v6, 16, v35
	v_and_b32_e32 v7, 0xffff0000, v35
	v_cvt_pk_bf16_f32 v4, v2, v3
	v_lshlrev_b32_e32 v2, 16, v9
	v_and_b32_e32 v3, 0xffff0000, v9
	v_pk_mul_f32 v[8:9], v[48:49], v[6:7]
	v_pk_mul_f32 v[6:7], v[56:57], v[6:7]
	v_pk_fma_f32 v[8:9], v[56:57], v[2:3], v[8:9]
	v_pk_fma_f32 v[2:3], v[48:49], v[2:3], v[6:7] neg_lo:[0,0,1] neg_hi:[0,0,1]
	v_pk_mul_f32 v[0:1], v[0:1], s[76:77] op_sel_hi:[1,0]
	v_pk_mul_f32 v[2:3], v[2:3], s[76:77] op_sel_hi:[1,0]
	v_cvt_pk_bf16_f32 v0, v0, v1
	v_cvt_pk_bf16_f32 v1, v2, v3
	v_pk_mul_f32 v[2:3], v[8:9], s[76:77] op_sel_hi:[1,0]
	v_lshlrev_b32_e32 v6, 16, v36
	v_and_b32_e32 v7, 0xffff0000, v36
	v_cvt_pk_bf16_f32 v5, v2, v3
	v_lshlrev_b32_e32 v2, 16, v10
	v_and_b32_e32 v3, 0xffff0000, v10
	v_pk_mul_f32 v[8:9], v[42:43], v[6:7]
	v_pk_mul_f32 v[6:7], v[50:51], v[6:7]
	v_pk_fma_f32 v[8:9], v[50:51], v[2:3], v[8:9]
	v_pk_fma_f32 v[2:3], v[42:43], v[2:3], v[6:7] neg_lo:[0,0,1] neg_hi:[0,0,1]
	v_pk_mul_f32 v[6:7], v[8:9], s[76:77] op_sel_hi:[1,0]
	v_lshlrev_b32_e32 v8, 16, v11
	v_and_b32_e32 v9, 0xffff0000, v11
	v_lshlrev_b32_e32 v10, 16, v37
	v_and_b32_e32 v11, 0xffff0000, v37
	v_pk_mul_f32 v[12:13], v[44:45], v[10:11]
	v_pk_mul_f32 v[10:11], v[52:53], v[10:11]
	v_pk_fma_f32 v[12:13], v[52:53], v[8:9], v[12:13]
	v_pk_fma_f32 v[8:9], v[44:45], v[8:9], v[10:11] neg_lo:[0,0,1] neg_hi:[0,0,1]
	v_pk_mul_f32 v[2:3], v[2:3], s[76:77] op_sel_hi:[1,0]
	v_pk_mul_f32 v[8:9], v[8:9], s[76:77] op_sel_hi:[1,0]
	v_cvt_pk_bf16_f32 v2, v2, v3
	v_cvt_pk_bf16_f32 v3, v8, v9
	v_pk_mul_f32 v[8:9], v[12:13], s[76:77] op_sel_hi:[1,0]
	v_cvt_pk_bf16_f32 v6, v6, v7
	v_cvt_pk_bf16_f32 v7, v8, v9
	v_and_b32_e32 v8, 0x78, v91
	v_lshlrev_b32_e32 v176, 1, v8
	ds_write_b128 v40, v[0:3] offset:34816
	ds_write_b128 v41, v[4:7] offset:34816
	v_lshl_add_u64 v[0:1], s[16:17], 0, v[176:177]
	v_lshl_add_u64 v[4:5], v[0:1], 0, s[36:37]
	v_lshlrev_b64 v[0:1], 14, v[58:59]
	v_lshl_add_u64 v[6:7], v[4:5], 0, v[0:1]
	v_add_u32_e32 v0, 0x200, v66
	v_ashrrev_i32_e32 v56, 4, v0
	v_ashrrev_i32_e32 v57, 31, v56
	v_lshlrev_b64 v[0:1], 14, v[56:57]
	v_lshl_add_u64 v[2:3], v[4:5], 0, v[0:1]
	v_add_u32_e32 v0, 0x400, v66
	v_add_u32_e32 v9, 0x600, v66
	v_ashrrev_i32_e32 v54, 4, v0
	v_ashrrev_i32_e32 v52, 4, v9
	v_ashrrev_i32_e32 v55, 31, v54
	v_ashrrev_i32_e32 v53, 31, v52
	v_lshlrev_b64 v[0:1], 14, v[54:55]
	v_lshlrev_b64 v[10:11], 14, v[52:53]
	v_mov_b32_e32 v9, s82
	v_lshl_add_u64 v[0:1], v[4:5], 0, v[0:1]
	v_lshl_add_u64 v[4:5], v[4:5], 0, v[10:11]
	v_mad_u32_u24 v10, v8, s38, v9
	v_lshlrev_b32_e32 v9, 1, v58
	v_lshlrev_b32_e32 v8, 1, v134
	v_and_b32_e32 v9, 14, v9
	v_add3_u32 v11, v10, v8, v9
	global_load_dwordx4 v[150:153], v[6:7], off
	global_load_dwordx4 v[154:157], v[2:3], off
	global_load_dwordx4 v[158:161], v[0:1], off
	global_load_dwordx4 v[162:165], v[4:5], off
	s_waitcnt vmcnt(0)
	v_mov_b32_e32 v6, v150
	v_mov_b32_e32 v7, v151
	v_mov_b32_e32 v8, v152
	v_mov_b32_e32 v9, v153
	ds_write_b16 v11, v6
	ds_write_b16_d16_hi v11, v6 offset:272
	ds_write_b16 v11, v7 offset:544
	ds_write_b16_d16_hi v11, v7 offset:816
	ds_write_b16 v11, v8 offset:1088
	ds_write_b16_d16_hi v11, v8 offset:1360
	ds_write_b16 v11, v9 offset:1632
	ds_write_b16_d16_hi v11, v9 offset:1904
	v_bitop3_b32 v135, v56, s0, v91 bitop3:0x48
	v_lshlrev_b32_e32 v7, 1, v56
	v_lshlrev_b32_e32 v6, 1, v135
	v_and_b32_e32 v7, 14, v7
	v_add3_u32 v11, v10, v6, v7
	s_nop 0
	v_mov_b32_e32 v6, v154
	v_mov_b32_e32 v7, v155
	v_mov_b32_e32 v8, v156
	v_mov_b32_e32 v9, v157
	ds_write_b16 v11, v6
	ds_write_b16_d16_hi v11, v6 offset:272
	ds_write_b16 v11, v7 offset:544
	ds_write_b16_d16_hi v11, v7 offset:816
	ds_write_b16 v11, v8 offset:1088
	ds_write_b16_d16_hi v11, v8 offset:1360
	ds_write_b16 v11, v9 offset:1632
	s_nop 0
	ds_write_b16_d16_hi v11, v9 offset:1904
	v_bitop3_b32 v136, v54, s0, v91 bitop3:0x48
	v_lshlrev_b32_e32 v9, 1, v54
	v_lshlrev_b32_e32 v8, 1, v136
	v_and_b32_e32 v9, 14, v9
	v_add3_u32 v8, v10, v8, v9
	s_nop 0
	v_mov_b32_e32 v0, v158
	v_mov_b32_e32 v1, v159
	v_mov_b32_e32 v2, v160
	v_mov_b32_e32 v3, v161
	ds_write_b16 v8, v0
	ds_write_b16_d16_hi v8, v0 offset:272
	ds_write_b16 v8, v1 offset:544
	ds_write_b16_d16_hi v8, v1 offset:816
	ds_write_b16 v8, v2 offset:1088
	ds_write_b16_d16_hi v8, v2 offset:1360
	ds_write_b16 v8, v3 offset:1632
	ds_write_b16_d16_hi v8, v3 offset:1904
	v_bitop3_b32 v133, v52, s0, v91 bitop3:0x48
	v_lshlrev_b32_e32 v1, 1, v52
	v_lshlrev_b32_e32 v0, 1, v133
	v_and_b32_e32 v1, 14, v1
	v_add3_u32 v0, v10, v0, v1
	v_lshlrev_b32_e32 v69, 4, v19
	s_nop 0
	v_mov_b32_e32 v4, v162
	v_mov_b32_e32 v5, v163
	v_mov_b32_e32 v6, v164
	v_mov_b32_e32 v7, v165
	ds_write_b16 v0, v4
	ds_write_b16_d16_hi v0, v4 offset:272
	ds_write_b16 v0, v5 offset:544
	ds_write_b16_d16_hi v0, v5 offset:816
	ds_write_b16 v0, v6 offset:1088
	ds_write_b16_d16_hi v0, v6 offset:1360
	ds_write_b16 v0, v7 offset:1632
	ds_write_b16_d16_hi v0, v7 offset:1904
	v_or_b32_e32 v0, v69, v68
	v_lshrrev_b32_e32 v8, 1, v66
	v_and_b32_e32 v16, 24, v8
	v_mul_lo_u32 v50, v0, s1
	v_bitop3_b32 v51, v69, s0, v68 bitop3:0xc8
	v_xad_u32 v0, v51, v16, v50
	v_lshl_add_u32 v53, v0, 1, 0
	s_waitcnt lgkmcnt(0)
	s_barrier
; #define LAS __attribute__((address_space(3)))
; DI void mma16(f32x4 (&acc)[8], const LAS unsigned char* At, int arow0, const LAS unsigned char* Bt, int lane) {
;     const int l15 = lane & 15, quad = lane >> 4;
; #pragma unroll
;     for (int ks = 0; ks < 4; ++ks) {
;         const bf16x8 a = *(const LAS bf16x8*)(At + sw(arow0 + l15, 32 * ks + 8 * quad) * 2);
; #pragma unroll
;         for (int cg = 0; cg < 8; ++cg) { const bf16x8 b = *(const LAS bf16x8*)(Bt + sw(16 * cg + l15, 32 * ks + 8 * quad) * 2);
;             acc[cg] = __builtin_amdgcn_mfma_f32_16x16x32_bf16(a, b, acc[cg], 0, 0, 0); }
;     }
; }
	v_and_b32_e32 v19, 8, v66
	ds_read_b128 v[0:3], v53
	v_bitop3_b32 v4, v8, v19, 24 bitop3:0x6c
	v_bitop3_b32 v8, v141, v8, 24 bitop3:0x28
	v_mad_u32_u24 v21, v68, s1, v220
	v_bitop3_b32 v12, v114, v16, 40 bitop3:0x6c
	v_bitop3_b32 v22, v95, v16, 56 bitop3:0x6c
	v_bitop3_b32 v26, v112, v16, s39 bitop3:0x6c
	v_bitop3_b32 v30, v110, v16, s40 bitop3:0x6c
	v_bitop3_b32 v34, v108, v16, s41 bitop3:0x6c
	v_bitop3_b32 v18, v100, v16, s0 bitop3:0x6c
	v_add_lshl_u32 v104, v4, v17, 1
	v_add_lshl_u32 v105, v8, v20, 1
	v_add_lshl_u32 v106, v12, v21, 1
	v_add_lshl_u32 v107, v22, v96, 1
	v_add_lshl_u32 v109, v26, v97, 1
	v_add_lshl_u32 v111, v30, v98, 1
	v_add_lshl_u32 v113, v34, v99, 1
	v_add_lshl_u32 v115, v18, v101, 1
	v_add_u32_e32 v55, 0, v104
	v_add_u32_e32 v57, 0, v105
	v_add_u32_e32 v59, 0, v106
	v_add_u32_e32 v61, 0, v107
	v_add_u32_e32 v62, 0, v109
	v_add_u32_e32 v63, 0, v111
	v_add_u32_e32 v70, 0, v113
	v_add_u32_e32 v71, 0, v115
	ds_read_b128 v[4:7], v55 offset:34816
	ds_read_b128 v[8:11], v57 offset:34816
	ds_read_b128 v[12:15], v59 offset:34816
	ds_read_b128 v[22:25], v61 offset:34816
	ds_read_b128 v[26:29], v62 offset:34816
	ds_read_b128 v[30:33], v63 offset:34816
	ds_read_b128 v[34:37], v70 offset:34816
	ds_read_b128 v[38:41], v71 offset:34816
	v_bitop3_b32 v42, v16, v19, 32 bitop3:0x36
	v_add_lshl_u32 v116, v42, v17, 1
	v_or_b32_e32 v18, 32, v16
	v_add_u32_e32 v73, 0, v116
	s_waitcnt lgkmcnt(7)
	v_mfma_f32_16x16x32_bf16 v[4:7], v[0:3], v[4:7], 0
	ds_read_b128 v[42:45], v73 offset:34816
	v_or_b32_e32 v102, 0x60, v16
	v_mul_lo_u32 v58, v58, s1
	s_waitcnt lgkmcnt(7)
	v_mfma_f32_16x16x32_bf16 v[8:11], v[0:3], v[8:11], 0
	v_add_lshl_u32 v58, v134, v58, 1
	s_waitcnt lgkmcnt(6)
	v_mfma_f32_16x16x32_bf16 v[12:15], v[0:3], v[12:15], 0
	s_waitcnt lgkmcnt(5)
	v_mfma_f32_16x16x32_bf16 v[22:25], v[0:3], v[22:25], 0
	s_waitcnt lgkmcnt(4)
	v_mfma_f32_16x16x32_bf16 v[26:29], v[0:3], v[26:29], 0
	s_waitcnt lgkmcnt(3)
	v_mfma_f32_16x16x32_bf16 v[30:33], v[0:3], v[30:33], 0
	s_waitcnt lgkmcnt(2)
	v_mfma_f32_16x16x32_bf16 v[34:37], v[0:3], v[34:37], 0
	s_waitcnt lgkmcnt(1)
	v_mfma_f32_16x16x32_bf16 v[0:3], v[0:3], v[38:41], 0
	v_xad_u32 v38, v51, v18, v50
	v_lshl_add_u32 v72, v38, 1, 0
	ds_read_b128 v[38:41], v72
	s_waitcnt lgkmcnt(0)
	v_mfma_f32_16x16x32_bf16 v[4:7], v[38:41], v[42:45], v[4:7]
	v_bitop3_b32 v42, v141, v18, 24 bitop3:0x6c
	v_add_lshl_u32 v117, v42, v20, 1
	v_add_u32_e32 v74, 0, v117
	ds_read_b128 v[42:45], v74 offset:34816
	s_waitcnt lgkmcnt(0)
	v_mfma_f32_16x16x32_bf16 v[8:11], v[38:41], v[42:45], v[8:11]
	v_bitop3_b32 v42, v114, v18, 40 bitop3:0x6c
	v_add_lshl_u32 v118, v42, v21, 1
	v_add_u32_e32 v75, 0, v118
	ds_read_b128 v[42:45], v75 offset:34816
	s_waitcnt lgkmcnt(0)
	v_mfma_f32_16x16x32_bf16 v[12:15], v[38:41], v[42:45], v[12:15]
	v_bitop3_b32 v42, v95, v18, 56 bitop3:0x6c
	v_add_lshl_u32 v119, v42, v96, 1
	v_add_u32_e32 v76, 0, v119
	ds_read_b128 v[42:45], v76 offset:34816
	s_waitcnt lgkmcnt(0)
	v_mfma_f32_16x16x32_bf16 v[22:25], v[38:41], v[42:45], v[22:25]
	v_bitop3_b32 v42, v112, v18, s39 bitop3:0x6c
	v_add_lshl_u32 v120, v42, v97, 1
	v_add_u32_e32 v77, 0, v120
	ds_read_b128 v[42:45], v77 offset:34816
	s_waitcnt lgkmcnt(0)
	v_mfma_f32_16x16x32_bf16 v[26:29], v[38:41], v[42:45], v[26:29]
	v_bitop3_b32 v42, v110, v18, s40 bitop3:0x6c
	v_add_lshl_u32 v121, v42, v98, 1
	v_add_u32_e32 v78, 0, v121
	ds_read_b128 v[42:45], v78 offset:34816
	s_waitcnt lgkmcnt(0)
	v_mfma_f32_16x16x32_bf16 v[42:45], v[38:41], v[42:45], v[30:33]
	s_nop 2
	v_bitop3_b32 v30, v108, v18, s41 bitop3:0x6c
	v_add_lshl_u32 v122, v30, v99, 1
	v_add_u32_e32 v79, 0, v122
	ds_read_b128 v[30:33], v79 offset:34816
	v_bitop3_b32 v18, v100, v18, s0 bitop3:0x6c
	v_add_lshl_u32 v123, v18, v101, 1
	v_add_u32_e32 v80, 0, v123
	s_waitcnt lgkmcnt(0)
	v_mfma_f32_16x16x32_bf16 v[46:49], v[38:41], v[30:33], v[34:37]
	ds_read_b128 v[30:33], v80 offset:34816
	v_or_b32_e32 v18, 64, v16
	s_waitcnt lgkmcnt(0)
	v_mfma_f32_16x16x32_bf16 v[142:145], v[38:41], v[30:33], v[0:3]
	s_nop 2
	v_xad_u32 v0, v51, v18, v50
	v_lshl_add_u32 v81, v0, 1, 0
	ds_read_b128 v[146:149], v81
	v_bitop3_b32 v0, v16, v19, 64 bitop3:0x36
	v_add_lshl_u32 v124, v0, v17, 1
	v_add_u32_e32 v82, 0, v124
	ds_read_b128 v[0:3], v82 offset:34816
	s_waitcnt lgkmcnt(0)
	v_mfma_f32_16x16x32_bf16 v[0:3], v[146:149], v[0:3], v[4:7]
	s_nop 2
	v_bitop3_b32 v4, v141, v18, 24 bitop3:0x6c
	v_add_lshl_u32 v125, v4, v20, 1
	v_add_u32_e32 v83, 0, v125
	ds_read_b128 v[4:7], v83 offset:34816
	s_waitcnt lgkmcnt(0)
	v_mfma_f32_16x16x32_bf16 v[4:7], v[146:149], v[4:7], v[8:11]
	s_nop 2
	v_bitop3_b32 v8, v114, v18, 40 bitop3:0x6c
	v_add_lshl_u32 v126, v8, v21, 1
	v_add_u32_e32 v84, 0, v126
	ds_read_b128 v[8:11], v84 offset:34816
	s_waitcnt lgkmcnt(0)
	v_mfma_f32_16x16x32_bf16 v[8:11], v[146:149], v[8:11], v[12:15]
	s_nop 2
	v_bitop3_b32 v12, v95, v18, 56 bitop3:0x6c
	v_add_lshl_u32 v127, v12, v96, 1
	v_add_u32_e32 v85, 0, v127
	ds_read_b128 v[12:15], v85 offset:34816
	s_waitcnt lgkmcnt(0)
	v_mfma_f32_16x16x32_bf16 v[12:15], v[146:149], v[12:15], v[22:25]
	s_nop 2
	v_bitop3_b32 v22, v112, v18, s39 bitop3:0x6c
	v_add_lshl_u32 v128, v22, v97, 1
	v_add_u32_e32 v86, 0, v128
	ds_read_b128 v[22:25], v86 offset:34816
	s_waitcnt lgkmcnt(0)
	v_mfma_f32_16x16x32_bf16 v[32:35], v[146:149], v[22:25], v[26:29]
	v_bitop3_b32 v22, v110, v18, s40 bitop3:0x6c
	v_add_lshl_u32 v129, v22, v98, 1
	v_add_u32_e32 v87, 0, v129
	ds_read_b128 v[22:25], v87 offset:34816
	s_waitcnt lgkmcnt(0)
; #define LAS __attribute__((address_space(3)))
; DI void out_unit(const Inputs& in, int l, unsigned char* ws, int half, int u, LAS unsigned char* lds, int tid) {
;     ...
;     zero8(F); mma16(F, Qt, 16 * wave, Kt, lane);
; #pragma unroll
;     for (int cg = 0; cg < 8; ++cg)
; #pragma unroll
;         for (int r = 0; r < 4; ++r) { const int i = 16 * wave + 4 * quad + r, j = 16 * cg + l15, df = i - j;
;             const float fac = df >= 0 ? __expf((float)df * lgf) : __expf((float)(-df) * lgb);
;             ((LAS bf16_t*)Ps)[sw(4 * quad + r, j)] = f2bf(F[cg][r] * fac); }
	v_mfma_f32_16x16x32_bf16 v[36:39], v[146:149], v[22:25], v[42:45]
	v_bitop3_b32 v22, v108, v18, s41 bitop3:0x6c
	v_add_lshl_u32 v130, v22, v99, 1
	v_add_u32_e32 v88, 0, v130
	ds_read_b128 v[22:25], v88 offset:34816
	v_bitop3_b32 v18, v100, v18, s0 bitop3:0x6c
	v_bitop3_b32 v16, v16, v19, s13 bitop3:0x36
	v_add_lshl_u32 v131, v18, v101, 1
	v_xad_u32 v18, v51, v102, v50
	v_add_lshl_u32 v132, v16, v17, 1
	v_add_u32_e32 v89, 0, v131
	v_lshl_add_u32 v90, v18, 1, 0
	v_add_u32_e32 v92, 0, v132
	ds_read_b128 v[16:19], v92 offset:34816
	s_waitcnt lgkmcnt(1)
	v_mfma_f32_16x16x32_bf16 v[40:43], v[146:149], v[22:25], v[46:49]
	ds_read_b128 v[22:25], v89 offset:34816
	s_ashr_i32 s13, s12, 31
	s_lshl_b64 s[16:17], s[12:13], 15
	ds_read_b128 v[48:51], v90
	s_waitcnt lgkmcnt(0)
	v_mfma_f32_16x16x32_bf16 v[28:31], v[48:51], v[16:19], v[0:3]
	s_nop 2
	v_bitop3_b32 v0, v141, v102, 24 bitop3:0x6c
	v_add_lshl_u32 v137, v0, v20, 1
	v_add_u32_e32 v93, 0, v137
	ds_read_b128 v[0:3], v93 offset:34816
	v_mfma_f32_16x16x32_bf16 v[44:47], v[146:149], v[22:25], v[142:145]
	s_add_u32 s16, s22, s16
	s_addc_u32 s17, s23, s17
	s_waitcnt lgkmcnt(0)
	v_mfma_f32_16x16x32_bf16 v[24:27], v[48:51], v[0:3], v[4:7]
	v_bitop3_b32 v0, v114, v102, 40 bitop3:0x6c
	v_add_lshl_u32 v138, v0, v21, 1
	v_add_u32_e32 v94, 0, v138
	ds_read_b128 v[0:3], v94 offset:34816
	s_waitcnt lgkmcnt(0)
	v_mfma_f32_16x16x32_bf16 v[20:23], v[48:51], v[0:3], v[8:11]
	v_bitop3_b32 v0, v95, v102, 56 bitop3:0x6c
	v_add_lshl_u32 v139, v0, v96, 1
	v_add_u32_e32 v95, 0, v139
	ds_read_b128 v[0:3], v95 offset:34816
	s_waitcnt lgkmcnt(0)
	v_mfma_f32_16x16x32_bf16 v[16:19], v[48:51], v[0:3], v[12:15]
	v_bitop3_b32 v0, v112, v102, s39 bitop3:0x6c
	v_add_lshl_u32 v140, v0, v97, 1
	v_add_u32_e32 v96, 0, v140
	ds_read_b128 v[0:3], v96 offset:34816
	s_waitcnt lgkmcnt(0)
	v_mfma_f32_16x16x32_bf16 v[12:15], v[48:51], v[0:3], v[32:35]
	v_bitop3_b32 v0, v110, v102, s40 bitop3:0x6c
	s_nop 1
	v_add_lshl_u32 v32, v0, v98, 1
	v_add_u32_e32 v97, 0, v32
	ds_read_b128 v[0:3], v97 offset:34816
	s_waitcnt lgkmcnt(0)
	v_mfma_f32_16x16x32_bf16 v[8:11], v[48:51], v[0:3], v[36:39]
	v_bitop3_b32 v0, v108, v102, s41 bitop3:0x6c
	v_add_lshl_u32 v33, v0, v99, 1
	v_add_u32_e32 v98, 0, v33
	ds_read_b128 v[0:3], v98 offset:34816
	v_lshrrev_b32_e32 v37, 2, v66
	s_waitcnt lgkmcnt(0)
	v_mfma_f32_16x16x32_bf16 v[4:7], v[48:51], v[0:3], v[40:43]
	v_bitop3_b32 v0, v100, v102, s0 bitop3:0x6c
	v_and_b32_e32 v36, 12, v37
	v_add_lshl_u32 v34, v0, v101, 1
	v_or_b32_e32 v101, v36, v69
	v_sub_u32_e32 v38, v101, v68
	v_sub_u32_e32 v39, 0, v38
	v_max_i32_e32 v39, v38, v39
	v_cvt_f32_u32_e32 v39, v39
	v_cmp_gt_i32_e32 vcc, 0, v38
	v_add_u32_e32 v99, 0, v34
	ds_read_b128 v[0:3], v99 offset:34816
	v_cndmask_b32_e32 v38, v60, v67, vcc
	v_mul_f32_e32 v38, v38, v39
	v_mul_f32_e32 v38, 0xbfb8aa3b, v38
	v_exp_f32_e32 v38, v38
	v_and_b32_e32 v35, 7, v66
	v_bitop3_b32 v37, v37, 8, v66 bitop3:0x48
	v_lshl_add_u32 v35, v35, 1, v65
	v_lshlrev_b32_e32 v37, 1, v37
	v_mul_f32_e32 v28, v38, v28
	v_mul_u32_u24_e32 v103, 0x110, v36
	s_waitcnt lgkmcnt(0)
	v_mfma_f32_16x16x32_bf16 v[0:3], v[48:51], v[0:3], v[44:47]
	v_cvt_pk_bf16_f32 v28, v28, s0
	v_add3_u32 v37, v35, v37, v103
	v_or_b32_e32 v48, 1, v101
	ds_write_b16 v37, v28
	v_sub_u32_e32 v28, v48, v68
	v_sub_u32_e32 v38, 0, v28
	v_max_i32_e32 v38, v28, v38
	v_cvt_f32_u32_e32 v38, v38
	v_cmp_gt_i32_e32 vcc, 0, v28
	v_or_b32_e32 v102, 2, v101
	v_or_b32_e32 v100, 3, v101
	v_cndmask_b32_e32 v28, v60, v67, vcc
	v_mul_f32_e32 v28, v28, v38
	v_mul_f32_e32 v28, 0xbfb8aa3b, v28
	v_exp_f32_e32 v28, v28
	v_add_u32_e32 v50, s82, v113
	v_add_u32_e32 v49, s82, v115
	v_add_u32_e32 v51, s82, v116
	v_mul_f32_e32 v28, v28, v29
	v_cvt_pk_bf16_f32 v28, v28, s0
	ds_write_b16 v37, v28 offset:272
	v_sub_u32_e32 v28, v102, v68
	v_sub_u32_e32 v29, 0, v28
	v_max_i32_e32 v29, v28, v29
	v_cvt_f32_u32_e32 v29, v29
	v_cmp_gt_i32_e32 vcc, 0, v28
	v_add_u32_e32 v113, s82, v121
	v_add_u32_e32 v115, s82, v122
	v_cndmask_b32_e32 v28, v60, v67, vcc
	v_mul_f32_e32 v28, v28, v29
	v_mul_f32_e32 v28, 0xbfb8aa3b, v28
	v_exp_f32_e32 v28, v28
	v_add_u32_e32 v121, s82, v128
	v_add_u32_e32 v122, s82, v129
	v_add_u32_e32 v128, s82, v139
	v_mul_f32_e32 v28, v28, v30
	v_cvt_pk_bf16_f32 v28, v28, s0
	ds_write_b16 v37, v28 offset:544
	v_sub_u32_e32 v28, v100, v68
	v_sub_u32_e32 v29, 0, v28
	v_max_i32_e32 v29, v28, v29
	v_cvt_f32_u32_e32 v29, v29
	v_cmp_gt_i32_e32 vcc, 0, v28
	v_add_u32_e32 v129, s82, v140
	s_nop 0
	v_cndmask_b32_e32 v28, v60, v67, vcc
	v_mul_f32_e32 v28, v28, v29
	v_sub_u32_e32 v29, v101, v141
	v_sub_u32_e32 v30, 0, v29
	v_max_i32_e32 v30, v29, v30
	v_cvt_f32_u32_e32 v30, v30
	v_mul_f32_e32 v28, 0xbfb8aa3b, v28
	v_cmp_gt_i32_e32 vcc, 0, v29
	v_exp_f32_e32 v28, v28
	s_nop 0
	v_cndmask_b32_e32 v29, v60, v67, vcc
	v_mul_f32_e32 v29, v29, v30
	v_mul_f32_e32 v29, 0xbfb8aa3b, v29
	v_exp_f32_e32 v29, v29
	v_mul_f32_e32 v28, v28, v31
	v_cvt_pk_bf16_f32 v28, v28, s0
	ds_write_b16 v37, v28 offset:816
	v_bitop3_b32 v28, v141, 24, v36 bitop3:0x48
	v_lshlrev_b32_e32 v28, 1, v28
	v_mul_f32_e32 v24, v29, v24
	v_cvt_pk_bf16_f32 v24, v24, s0
	v_add3_u32 v28, v35, v28, v103
	ds_write_b16 v28, v24
	v_sub_u32_e32 v24, v48, v141
	v_sub_u32_e32 v29, 0, v24
	v_max_i32_e32 v29, v24, v29
	v_cvt_f32_u32_e32 v29, v29
	v_cmp_gt_i32_e32 vcc, 0, v24
	s_nop 1
	v_cndmask_b32_e32 v24, v60, v67, vcc
	v_mul_f32_e32 v24, v24, v29
	v_mul_f32_e32 v24, 0xbfb8aa3b, v24
	v_exp_f32_e32 v24, v24
	s_nop 0
	v_mul_f32_e32 v24, v24, v25
	v_cvt_pk_bf16_f32 v24, v24, s0
	ds_write_b16 v28, v24 offset:272
	v_sub_u32_e32 v24, v102, v141
	v_sub_u32_e32 v25, 0, v24
	v_max_i32_e32 v25, v24, v25
; #define LAS __attribute__((address_space(3)))
; DI void out_unit(const Inputs& in, int l, unsigned char* ws, int half, int u, LAS unsigned char* lds, int tid) {
;     ...
; #pragma unroll
;     for (int cg = 0; cg < 8; ++cg)
; #pragma unroll
;         for (int r = 0; r < 4; ++r) { const int i = 16 * wave + 4 * quad + r, j = 16 * cg + l15, df = i - j;
;             const float fac = df >= 0 ? __expf((float)df * lgf) : __expf((float)(-df) * lgb);
;             ((LAS bf16_t*)Ps)[sw(4 * quad + r, j)] = f2bf(F[cg][r] * fac); }
	v_cvt_f32_u32_e32 v25, v25
	v_cmp_gt_i32_e32 vcc, 0, v24
	s_nop 1
	v_cndmask_b32_e32 v24, v60, v67, vcc
	v_mul_f32_e32 v24, v24, v25
	v_mul_f32_e32 v24, 0xbfb8aa3b, v24
	v_exp_f32_e32 v24, v24
	s_nop 0
	v_mul_f32_e32 v24, v24, v26
	v_cvt_pk_bf16_f32 v24, v24, s0
	ds_write_b16 v28, v24 offset:544
	v_sub_u32_e32 v24, v100, v141
	v_sub_u32_e32 v25, 0, v24
	v_max_i32_e32 v25, v24, v25
	v_cvt_f32_u32_e32 v25, v25
	v_cmp_gt_i32_e32 vcc, 0, v24
	s_nop 1
	v_cndmask_b32_e32 v24, v60, v67, vcc
	v_mul_f32_e32 v24, v24, v25
	v_sub_u32_e32 v25, v101, v114
	v_sub_u32_e32 v26, 0, v25
	v_max_i32_e32 v26, v25, v26
	v_cvt_f32_u32_e32 v26, v26
	v_mul_f32_e32 v24, 0xbfb8aa3b, v24
	v_cmp_gt_i32_e32 vcc, 0, v25
	v_exp_f32_e32 v24, v24
	s_nop 0
	v_cndmask_b32_e32 v25, v60, v67, vcc
	v_mul_f32_e32 v25, v25, v26
	v_mul_f32_e32 v25, 0xbfb8aa3b, v25
	v_exp_f32_e32 v25, v25
	v_mul_f32_e32 v24, v24, v27
	v_cvt_pk_bf16_f32 v24, v24, s0
	ds_write_b16 v28, v24 offset:816
	v_bitop3_b32 v24, v114, 40, v36 bitop3:0x48
	v_lshlrev_b32_e32 v24, 1, v24
	v_mul_f32_e32 v20, v25, v20
	v_cvt_pk_bf16_f32 v20, v20, s0
	v_add3_u32 v24, v35, v24, v103
	ds_write_b16 v24, v20
	v_sub_u32_e32 v20, v48, v114
	v_sub_u32_e32 v25, 0, v20
	v_max_i32_e32 v25, v20, v25
	v_cvt_f32_u32_e32 v25, v25
	v_cmp_gt_i32_e32 vcc, 0, v20
	s_nop 1
	v_cndmask_b32_e32 v20, v60, v67, vcc
	v_mul_f32_e32 v20, v20, v25
	v_mul_f32_e32 v20, 0xbfb8aa3b, v20
	v_exp_f32_e32 v20, v20
	s_nop 0
	v_mul_f32_e32 v20, v20, v21
	v_cvt_pk_bf16_f32 v20, v20, s0
	ds_write_b16 v24, v20 offset:272
	v_sub_u32_e32 v20, v102, v114
	v_sub_u32_e32 v21, 0, v20
	v_max_i32_e32 v21, v20, v21
	v_cvt_f32_u32_e32 v21, v21
	v_cmp_gt_i32_e32 vcc, 0, v20
	s_nop 1
	v_cndmask_b32_e32 v20, v60, v67, vcc
	v_mul_f32_e32 v20, v20, v21
	v_mul_f32_e32 v20, 0xbfb8aa3b, v20
	v_exp_f32_e32 v20, v20
	s_nop 0
	v_mul_f32_e32 v20, v20, v22
	v_cvt_pk_bf16_f32 v20, v20, s0
	ds_write_b16 v24, v20 offset:544
	v_sub_u32_e32 v20, v100, v114
	v_sub_u32_e32 v21, 0, v20
	v_max_i32_e32 v21, v20, v21
	v_cvt_f32_u32_e32 v21, v21
	v_cmp_gt_i32_e32 vcc, 0, v20
	v_add_u32_e32 v114, s82, v104
	s_nop 0
	v_cndmask_b32_e32 v20, v60, v67, vcc
	v_mul_f32_e32 v20, v20, v21
	v_mul_f32_e32 v20, 0xbfb8aa3b, v20
	v_exp_f32_e32 v20, v20
	s_nop 0
	v_mul_f32_e32 v20, v20, v23
	v_cvt_pk_bf16_f32 v20, v20, s0
	ds_write_b16 v24, v20 offset:816
	v_or_b32_e32 v20, 48, v68
	v_sub_u32_e32 v22, v101, v20
	v_sub_u32_e32 v23, 0, v22
	v_max_i32_e32 v23, v22, v23
	v_cvt_f32_u32_e32 v23, v23
	v_cmp_gt_i32_e32 vcc, 0, v22
	v_bitop3_b32 v21, v20, 56, v36 bitop3:0x48
	v_lshlrev_b32_e32 v21, 1, v21
	v_cndmask_b32_e32 v22, v60, v67, vcc
	v_mul_f32_e32 v22, v22, v23
	v_mul_f32_e32 v22, 0xbfb8aa3b, v22
	v_exp_f32_e32 v22, v22
	v_add3_u32 v21, v35, v21, v103
	v_mul_f32_e32 v16, v22, v16
	v_cvt_pk_bf16_f32 v16, v16, s0
	ds_write_b16 v21, v16
	v_sub_u32_e32 v16, v48, v20
	v_sub_u32_e32 v22, 0, v16
	v_max_i32_e32 v22, v16, v22
	v_cvt_f32_u32_e32 v22, v22
	v_cmp_gt_i32_e32 vcc, 0, v16
	s_nop 1
	v_cndmask_b32_e32 v16, v60, v67, vcc
	v_mul_f32_e32 v16, v16, v22
	v_mul_f32_e32 v16, 0xbfb8aa3b, v16
	v_exp_f32_e32 v16, v16
	s_nop 0
	v_mul_f32_e32 v16, v16, v17
	v_cvt_pk_bf16_f32 v16, v16, s0
	ds_write_b16 v21, v16 offset:272
	v_sub_u32_e32 v16, v102, v20
	v_sub_u32_e32 v17, 0, v16
	v_max_i32_e32 v17, v16, v17
	v_cvt_f32_u32_e32 v17, v17
	v_cmp_gt_i32_e32 vcc, 0, v16
	s_nop 1
	v_cndmask_b32_e32 v16, v60, v67, vcc
	v_mul_f32_e32 v16, v16, v17
	v_mul_f32_e32 v16, 0xbfb8aa3b, v16
	v_exp_f32_e32 v16, v16
	s_nop 0
	v_mul_f32_e32 v16, v16, v18
	v_cvt_pk_bf16_f32 v16, v16, s0
	ds_write_b16 v21, v16 offset:544
	v_sub_u32_e32 v16, v100, v20
	v_sub_u32_e32 v17, 0, v16
	v_max_i32_e32 v17, v16, v17
	v_cvt_f32_u32_e32 v17, v17
	v_cmp_gt_i32_e32 vcc, 0, v16
	s_nop 1
	v_cndmask_b32_e32 v16, v60, v67, vcc
	v_mul_f32_e32 v16, v16, v17
	v_sub_u32_e32 v17, v101, v112
	v_sub_u32_e32 v18, 0, v17
	v_max_i32_e32 v18, v17, v18
	v_cvt_f32_u32_e32 v18, v18
	v_mul_f32_e32 v16, 0xbfb8aa3b, v16
	v_cmp_gt_i32_e32 vcc, 0, v17
	v_exp_f32_e32 v16, v16
	s_nop 0
	v_cndmask_b32_e32 v17, v60, v67, vcc
	v_mul_f32_e32 v17, v17, v18
	v_mul_f32_e32 v17, 0xbfb8aa3b, v17
	v_exp_f32_e32 v17, v17
	v_mul_f32_e32 v16, v16, v19
	v_cvt_pk_bf16_f32 v16, v16, s0
	ds_write_b16 v21, v16 offset:816
	v_bitop3_b32 v16, v112, s39, v36 bitop3:0x48
	v_lshlrev_b32_e32 v16, 1, v16
	v_mul_f32_e32 v12, v17, v12
	v_cvt_pk_bf16_f32 v12, v12, s0
	v_add3_u32 v16, v35, v16, v103
	ds_write_b16 v16, v12
	v_sub_u32_e32 v12, v48, v112
	v_sub_u32_e32 v17, 0, v12
	v_max_i32_e32 v17, v12, v17
	v_cvt_f32_u32_e32 v17, v17
	v_cmp_gt_i32_e32 vcc, 0, v12
	s_nop 1
	v_cndmask_b32_e32 v12, v60, v67, vcc
	v_mul_f32_e32 v12, v12, v17
	v_mul_f32_e32 v12, 0xbfb8aa3b, v12
	v_exp_f32_e32 v12, v12
	s_nop 0
	v_mul_f32_e32 v12, v12, v13
	v_cvt_pk_bf16_f32 v12, v12, s0
	ds_write_b16 v16, v12 offset:272
	v_sub_u32_e32 v12, v102, v112
	v_sub_u32_e32 v13, 0, v12
	v_max_i32_e32 v13, v12, v13
	v_cvt_f32_u32_e32 v13, v13
	v_cmp_gt_i32_e32 vcc, 0, v12
	s_nop 1
	v_cndmask_b32_e32 v12, v60, v67, vcc
	v_mul_f32_e32 v12, v12, v13
	v_mul_f32_e32 v12, 0xbfb8aa3b, v12
	v_exp_f32_e32 v12, v12
	s_nop 0
	v_mul_f32_e32 v12, v12, v14
	v_cvt_pk_bf16_f32 v12, v12, s0
	ds_write_b16 v16, v12 offset:544
	v_sub_u32_e32 v12, v100, v112
	v_sub_u32_e32 v13, 0, v12
	v_max_i32_e32 v13, v12, v13
	v_cvt_f32_u32_e32 v13, v13
	v_cmp_gt_i32_e32 vcc, 0, v12
	v_add_u32_e32 v112, s82, v105
	v_add_u32_e32 v105, s82, v117
	v_cndmask_b32_e32 v12, v60, v67, vcc
	v_mul_f32_e32 v12, v12, v13
	v_sub_u32_e32 v13, v101, v110
	v_sub_u32_e32 v14, 0, v13
	v_max_i32_e32 v14, v13, v14
	v_cvt_f32_u32_e32 v14, v14
	v_mul_f32_e32 v12, 0xbfb8aa3b, v12
; #define LAS __attribute__((address_space(3)))
; #define LDS_WAIT() asm volatile("s_waitcnt lgkmcnt(0)" ::: "memory")
; DI void out_unit(const Inputs& in, int l, unsigned char* ws, int half, int u, LAS unsigned char* lds, int tid) {
;     ...
; #pragma unroll
;     for (int cg = 0; cg < 8; ++cg)
; #pragma unroll
;         for (int r = 0; r < 4; ++r) { const int i = 16 * wave + 4 * quad + r, j = 16 * cg + l15, df = i - j;
;             const float fac = df >= 0 ? __expf((float)df * lgf) : __expf((float)(-df) * lgb);
;             ((LAS bf16_t*)Ps)[sw(4 * quad + r, j)] = f2bf(F[cg][r] * fac); }
;     LDS_WAIT();
;     zero8(O); mma16(O, Ps, 0, VTt, lane);
	v_cmp_gt_i32_e32 vcc, 0, v13
	v_exp_f32_e32 v12, v12
	v_add_u32_e32 v117, s82, v124
	v_cndmask_b32_e32 v13, v60, v67, vcc
	v_mul_f32_e32 v13, v13, v14
	v_mul_f32_e32 v13, 0xbfb8aa3b, v13
	v_exp_f32_e32 v13, v13
	v_mul_f32_e32 v12, v12, v15
	v_cvt_pk_bf16_f32 v12, v12, s0
	ds_write_b16 v16, v12 offset:816
	v_bitop3_b32 v12, v110, s40, v36 bitop3:0x48
	v_lshlrev_b32_e32 v12, 1, v12
	v_mul_f32_e32 v8, v13, v8
	v_cvt_pk_bf16_f32 v8, v8, s0
	v_add3_u32 v12, v35, v12, v103
	ds_write_b16 v12, v8
	v_sub_u32_e32 v8, v48, v110
	v_sub_u32_e32 v13, 0, v8
	v_max_i32_e32 v13, v8, v13
	v_cvt_f32_u32_e32 v13, v13
	v_cmp_gt_i32_e32 vcc, 0, v8
	s_nop 1
	v_cndmask_b32_e32 v8, v60, v67, vcc
	v_mul_f32_e32 v8, v8, v13
	v_mul_f32_e32 v8, 0xbfb8aa3b, v8
	v_exp_f32_e32 v8, v8
	s_nop 0
	v_mul_f32_e32 v8, v8, v9
	v_cvt_pk_bf16_f32 v8, v8, s0
	ds_write_b16 v12, v8 offset:272
	v_sub_u32_e32 v8, v102, v110
	v_sub_u32_e32 v9, 0, v8
	v_max_i32_e32 v9, v8, v9
	v_cvt_f32_u32_e32 v9, v9
	v_cmp_gt_i32_e32 vcc, 0, v8
	s_nop 1
	v_cndmask_b32_e32 v8, v60, v67, vcc
	v_mul_f32_e32 v8, v8, v9
	v_mul_f32_e32 v8, 0xbfb8aa3b, v8
	v_exp_f32_e32 v8, v8
	s_nop 0
	v_mul_f32_e32 v8, v8, v10
	v_cvt_pk_bf16_f32 v8, v8, s0
	ds_write_b16 v12, v8 offset:544
	v_sub_u32_e32 v8, v100, v110
	v_sub_u32_e32 v9, 0, v8
	v_max_i32_e32 v9, v8, v9
	v_cvt_f32_u32_e32 v9, v9
	v_cmp_gt_i32_e32 vcc, 0, v8
	v_add_u32_e32 v110, s82, v106
	v_add_u32_e32 v106, s82, v109
	v_cndmask_b32_e32 v8, v60, v67, vcc
	v_mul_f32_e32 v8, v8, v9
	v_sub_u32_e32 v9, v101, v108
	v_sub_u32_e32 v10, 0, v9
	v_max_i32_e32 v10, v9, v10
	v_cvt_f32_u32_e32 v10, v10
	v_mul_f32_e32 v8, 0xbfb8aa3b, v8
	v_cmp_gt_i32_e32 vcc, 0, v9
	v_exp_f32_e32 v8, v8
	v_add_u32_e32 v109, s82, v119
	v_cndmask_b32_e32 v9, v60, v67, vcc
	v_mul_f32_e32 v9, v9, v10
	v_mul_f32_e32 v9, 0xbfb8aa3b, v9
	v_exp_f32_e32 v9, v9
	v_mul_f32_e32 v8, v8, v11
	v_cvt_pk_bf16_f32 v8, v8, s0
	ds_write_b16 v12, v8 offset:816
	v_bitop3_b32 v8, v108, s41, v36 bitop3:0x48
	v_lshlrev_b32_e32 v8, 1, v8
	v_mul_f32_e32 v4, v9, v4
	v_cvt_pk_bf16_f32 v4, v4, s0
	v_add3_u32 v8, v35, v8, v103
	ds_write_b16 v8, v4
	v_sub_u32_e32 v4, v48, v108
	v_sub_u32_e32 v9, 0, v4
	v_max_i32_e32 v9, v4, v9
	v_cvt_f32_u32_e32 v9, v9
	v_cmp_gt_i32_e32 vcc, 0, v4
	v_add_u32_e32 v119, s82, v126
	v_add_u32_e32 v126, s82, v137
	v_cndmask_b32_e32 v4, v60, v67, vcc
	v_mul_f32_e32 v4, v4, v9
	v_mul_f32_e32 v4, 0xbfb8aa3b, v4
	v_exp_f32_e32 v4, v4
	s_nop 0
	v_mul_f32_e32 v4, v4, v5
	v_cvt_pk_bf16_f32 v4, v4, s0
	ds_write_b16 v8, v4 offset:272
	v_sub_u32_e32 v4, v102, v108
	v_sub_u32_e32 v5, 0, v4
	v_max_i32_e32 v5, v4, v5
	v_cvt_f32_u32_e32 v5, v5
	v_cmp_gt_i32_e32 vcc, 0, v4
	s_nop 1
	v_cndmask_b32_e32 v4, v60, v67, vcc
	v_mul_f32_e32 v4, v4, v5
	v_mul_f32_e32 v4, 0xbfb8aa3b, v4
	v_exp_f32_e32 v4, v4
	s_nop 0
	v_mul_f32_e32 v4, v4, v6
	v_cvt_pk_bf16_f32 v4, v4, s0
	ds_write_b16 v8, v4 offset:544
	v_sub_u32_e32 v4, v100, v108
	v_sub_u32_e32 v5, 0, v4
	v_max_i32_e32 v5, v4, v5
	v_cvt_f32_u32_e32 v5, v5
	v_cmp_gt_i32_e32 vcc, 0, v4
	v_add_u32_e32 v108, s82, v107
	v_add_u32_e32 v107, s82, v118
	v_cndmask_b32_e32 v4, v60, v67, vcc
	v_mul_f32_e32 v4, v4, v5
	v_mul_f32_e32 v4, 0xbfb8aa3b, v4
	v_exp_f32_e32 v4, v4
	v_add_u32_e32 v118, s82, v125
	v_add_u32_e32 v125, s82, v132
	v_mul_f32_e32 v4, v4, v7
	v_cvt_pk_bf16_f32 v4, v4, s0
	ds_write_b16 v8, v4 offset:816
	v_or_b32_e32 v4, 0x70, v68
	v_sub_u32_e32 v6, v101, v4
	v_sub_u32_e32 v7, 0, v6
	v_max_i32_e32 v7, v6, v7
	v_cvt_f32_u32_e32 v7, v7
	v_cmp_gt_i32_e32 vcc, 0, v6
	v_bitop3_b32 v5, v4, s0, v36 bitop3:0x48
	v_lshlrev_b32_e32 v5, 1, v5
	v_cndmask_b32_e32 v6, v60, v67, vcc
	v_mul_f32_e32 v6, v6, v7
	v_mul_f32_e32 v6, 0xbfb8aa3b, v6
	v_exp_f32_e32 v6, v6
	v_add3_u32 v5, v35, v5, v103
	v_add_u32_e32 v35, v65, v116
	v_add_u32_e32 v116, s82, v123
	v_mul_f32_e32 v0, v6, v0
	v_cvt_pk_bf16_f32 v0, v0, s0
	ds_write_b16 v5, v0
	v_sub_u32_e32 v0, v48, v4
	v_sub_u32_e32 v6, 0, v0
	v_max_i32_e32 v6, v0, v6
	v_cvt_f32_u32_e32 v6, v6
	v_cmp_gt_i32_e32 vcc, 0, v0
	v_add_u32_e32 v123, s82, v130
	v_add_u32_e32 v130, s82, v32
	v_cndmask_b32_e32 v0, v60, v67, vcc
	v_mul_f32_e32 v0, v0, v6
	v_mul_f32_e32 v0, 0xbfb8aa3b, v0
	v_exp_f32_e32 v0, v0
	v_cvt_f32_i32_e32 v48, v48
	v_mul_f32_e32 v0, v0, v1
	v_cvt_pk_bf16_f32 v0, v0, s0
	ds_write_b16 v5, v0 offset:272
	v_sub_u32_e32 v0, v102, v4
	v_sub_u32_e32 v1, 0, v0
	v_max_i32_e32 v1, v0, v1
	v_cvt_f32_u32_e32 v1, v1
	v_cmp_gt_i32_e32 vcc, 0, v0
	v_mul_f32_e32 v48, v48, v60
	v_mul_f32_e32 v48, 0xbfb8aa3b, v48
	v_cndmask_b32_e32 v0, v60, v67, vcc
	v_mul_f32_e32 v0, v0, v1
	v_mul_f32_e32 v0, 0xbfb8aa3b, v0
	v_exp_f32_e32 v0, v0
	v_exp_f32_e32 v48, v48
	v_mul_f32_e32 v0, v0, v2
	v_cvt_pk_bf16_f32 v0, v0, s0
	ds_write_b16 v5, v0 offset:544
	v_sub_u32_e32 v0, v100, v4
	v_sub_u32_e32 v1, 0, v0
	v_max_i32_e32 v1, v0, v1
	v_cvt_f32_u32_e32 v1, v1
	v_cmp_gt_i32_e32 vcc, 0, v0
	s_nop 1
	v_cndmask_b32_e32 v0, v60, v67, vcc
	v_mul_f32_e32 v0, v0, v1
	v_mul_f32_e32 v0, 0xbfb8aa3b, v0
	v_exp_f32_e32 v0, v0
	s_nop 0
	v_mul_f32_e32 v0, v0, v3
	v_cvt_pk_bf16_f32 v0, v0, s0
	ds_write_b16 v5, v0 offset:816
	s_waitcnt lgkmcnt(0)
	v_add_u32_e32 v0, v65, v104
	ds_read_b128 v[0:3], v0
	ds_read_b128 v[36:39], v49
	v_add_u32_e32 v104, s82, v111
	ds_read_b128 v[4:7], v114
	ds_read_b128 v[8:11], v112
	ds_read_b128 v[12:15], v110
	ds_read_b128 v[16:19], v108
	ds_read_b128 v[20:23], v106
	ds_read_b128 v[24:27], v104
	ds_read_b128 v[28:31], v50
	s_waitcnt lgkmcnt(6)
	v_mfma_f32_16x16x32_bf16 v[4:7], v[0:3], v[4:7], 0
	ds_read_b128 v[40:43], v51
	v_add_u32_e32 v111, s82, v120
	v_add_u32_e32 v120, s82, v127
	s_waitcnt lgkmcnt(6)
; #define LAS __attribute__((address_space(3)))
; DI void stage_state(LAS unsigned char* dst, const bf16_t* src, int tid) {
;     u32x4 wv[4];
; #pragma unroll
;     for (int k = 0; k < 4; ++k) { const int it = tid + 512 * k, e = it >> 4, d0 = (it & 15) * 8; wv[k] = *(const u32x4*)(src + e * 128 + d0); }
; #pragma unroll
;     for (int k = 0; k < 4; ++k) { const int it = tid + 512 * k, e = it >> 4, d0 = (it & 15) * 8; *(LAS u32x4*)(dst + sw(e, d0) * 2) = wv[k]; }
; }
; DI void mma16(f32x4 (&acc)[8], const LAS unsigned char* At, int arow0, const LAS unsigned char* Bt, int lane) {
;     const int l15 = lane & 15, quad = lane >> 4;
; #pragma unroll
;     for (int ks = 0; ks < 4; ++ks) {
;         const bf16x8 a = *(const LAS bf16x8*)(At + sw(arow0 + l15, 32 * ks + 8 * quad) * 2);
; #pragma unroll
;         for (int cg = 0; cg < 8; ++cg) { const bf16x8 b = *(const LAS bf16x8*)(Bt + sw(16 * cg + l15, 32 * ks + 8 * quad) * 2);
;             acc[cg] = __builtin_amdgcn_mfma_f32_16x16x32_bf16(a, b, acc[cg], 0, 0, 0); }
;     }
; }
; DI void out_unit(const Inputs& in, int l, unsigned char* ws, int half, int u, LAS unsigned char* lds, int tid) {
;     ...
;     zero8(O); mma16(O, Ps, 0, VTt, lane);
;     __syncthreads();
;     stage_state(Kt, SS + (size_t)(u * 2 + 0) * 16384, tid); stage_state(VTt, SS + (size_t)(u * 2 + 1) * 16384, tid);
;     __syncthreads();
	v_mfma_f32_16x16x32_bf16 v[8:11], v[0:3], v[8:11], 0
	v_add_u32_e32 v127, s82, v138
	s_waitcnt lgkmcnt(5)
	v_mfma_f32_16x16x32_bf16 v[12:15], v[0:3], v[12:15], 0
	s_waitcnt lgkmcnt(4)
	v_mfma_f32_16x16x32_bf16 v[16:19], v[0:3], v[16:19], 0
	s_waitcnt lgkmcnt(3)
	v_mfma_f32_16x16x32_bf16 v[20:23], v[0:3], v[20:23], 0
	s_waitcnt lgkmcnt(2)
	v_mfma_f32_16x16x32_bf16 v[24:27], v[0:3], v[24:27], 0
	s_waitcnt lgkmcnt(1)
	v_mfma_f32_16x16x32_bf16 v[28:31], v[0:3], v[28:31], 0
	v_mfma_f32_16x16x32_bf16 v[0:3], v[0:3], v[36:39], 0
	ds_read_b128 v[36:39], v35
	v_add_u32_e32 v35, v65, v124
	v_add_u32_e32 v124, s82, v131
	s_waitcnt lgkmcnt(0)
	v_mfma_f32_16x16x32_bf16 v[4:7], v[36:39], v[40:43], v[4:7]
	ds_read_b128 v[40:43], v105
	v_add_u32_e32 v131, s82, v33
	v_lshl_add_u64 v[32:33], s[16:17], 0, v[176:177]
	s_waitcnt lgkmcnt(0)
	v_mfma_f32_16x16x32_bf16 v[8:11], v[36:39], v[40:43], v[8:11]
	ds_read_b128 v[40:43], v107
	s_add_i32 s16, s12, 1
	s_ashr_i32 s17, s16, 31
	s_waitcnt lgkmcnt(0)
	v_mfma_f32_16x16x32_bf16 v[12:15], v[36:39], v[40:43], v[12:15]
	ds_read_b128 v[40:43], v109
	s_lshl_b64 s[16:17], s[16:17], 15
	s_add_u32 s16, s22, s16
	s_waitcnt lgkmcnt(0)
	v_mfma_f32_16x16x32_bf16 v[16:19], v[36:39], v[40:43], v[16:19]
	ds_read_b128 v[40:43], v111
	s_addc_u32 s17, s23, s17
	s_add_i32 s26, s26, s18
	s_waitcnt lgkmcnt(0)
	v_mfma_f32_16x16x32_bf16 v[20:23], v[36:39], v[40:43], v[20:23]
	ds_read_b128 v[40:43], v113
	s_add_i32 s12, s12, s25
	s_cmpk_gt_i32 s26, 0x1ff
	s_waitcnt lgkmcnt(0)
	v_mfma_f32_16x16x32_bf16 v[24:27], v[36:39], v[40:43], v[24:27]
	ds_read_b128 v[40:43], v115
	s_waitcnt lgkmcnt(0)
	v_mfma_f32_16x16x32_bf16 v[28:31], v[36:39], v[40:43], v[28:31]
	ds_read_b128 v[40:43], v116
	s_waitcnt lgkmcnt(0)
	v_mfma_f32_16x16x32_bf16 v[0:3], v[36:39], v[40:43], v[0:3]
	ds_read_b128 v[36:39], v35
	ds_read_b128 v[40:43], v117
	s_waitcnt lgkmcnt(0)
	v_mfma_f32_16x16x32_bf16 v[4:7], v[36:39], v[40:43], v[4:7]
	ds_read_b128 v[40:43], v118
	s_waitcnt lgkmcnt(0)
	v_mfma_f32_16x16x32_bf16 v[8:11], v[36:39], v[40:43], v[8:11]
	ds_read_b128 v[40:43], v119
	s_waitcnt lgkmcnt(0)
	v_mfma_f32_16x16x32_bf16 v[12:15], v[36:39], v[40:43], v[12:15]
	ds_read_b128 v[40:43], v120
	s_waitcnt lgkmcnt(0)
	v_mfma_f32_16x16x32_bf16 v[16:19], v[36:39], v[40:43], v[16:19]
	ds_read_b128 v[40:43], v121
	s_waitcnt lgkmcnt(0)
	v_mfma_f32_16x16x32_bf16 v[20:23], v[36:39], v[40:43], v[20:23]
	ds_read_b128 v[40:43], v122
	s_waitcnt lgkmcnt(0)
	v_mfma_f32_16x16x32_bf16 v[24:27], v[36:39], v[40:43], v[24:27]
	ds_read_b128 v[40:43], v123
	s_waitcnt lgkmcnt(0)
	v_mfma_f32_16x16x32_bf16 v[28:31], v[36:39], v[40:43], v[28:31]
	ds_read_b128 v[40:43], v124
	s_waitcnt lgkmcnt(0)
	v_mfma_f32_16x16x32_bf16 v[36:39], v[36:39], v[40:43], v[0:3]
	s_nop 2
	v_add_u32_e32 v0, v65, v132
	ds_read_b128 v[40:43], v0
	ds_read_b128 v[0:3], v125
	s_waitcnt lgkmcnt(0)
	v_mfma_f32_16x16x32_bf16 v[0:3], v[40:43], v[0:3], v[4:7]
	s_nop 2
	ds_read_b128 v[4:7], v126
	v_add_u32_e32 v132, s82, v34
	v_and_b32_e32 v34, 0xffffff80, v91
	s_waitcnt lgkmcnt(0)
	v_mfma_f32_16x16x32_bf16 v[4:7], v[40:43], v[4:7], v[8:11]
	v_ashrrev_i32_e32 v35, 31, v34
	s_nop 1
	ds_read_b128 v[8:11], v127
	v_add_u32_e32 v91, 0, v58
	s_waitcnt lgkmcnt(0)
	v_mfma_f32_16x16x32_bf16 v[8:11], v[40:43], v[8:11], v[12:15]
	s_nop 2
	ds_read_b128 v[12:15], v128
	s_waitcnt lgkmcnt(0)
	v_mfma_f32_16x16x32_bf16 v[12:15], v[40:43], v[12:15], v[16:19]
	s_nop 2
	ds_read_b128 v[16:19], v129
	s_waitcnt lgkmcnt(0)
	v_mfma_f32_16x16x32_bf16 v[16:19], v[40:43], v[16:19], v[20:23]
	s_nop 2
	ds_read_b128 v[20:23], v130
	s_waitcnt lgkmcnt(0)
	v_mfma_f32_16x16x32_bf16 v[20:23], v[40:43], v[20:23], v[24:27]
	s_nop 2
	ds_read_b128 v[24:27], v131
	s_waitcnt lgkmcnt(0)
	v_mfma_f32_16x16x32_bf16 v[24:27], v[40:43], v[24:27], v[28:31]
	s_nop 2
	ds_read_b128 v[28:31], v132
	s_waitcnt lgkmcnt(0)
	s_barrier
	v_mfma_f32_16x16x32_bf16 v[28:31], v[40:43], v[28:31], v[36:39]
	s_nop 2
	v_lshlrev_b64 v[36:37], 1, v[34:35]
	v_lshl_add_u64 v[38:39], v[32:33], 0, v[36:37]
	global_load_dwordx4 v[44:47], v[38:39], off
	v_add_u32_e32 v38, 0x1000, v34
	v_ashrrev_i32_e32 v39, 31, v38
	v_lshlrev_b64 v[38:39], 1, v[38:39]
	v_lshl_add_u64 v[40:41], v[32:33], 0, v[38:39]
	global_load_dwordx4 v[138:141], v[40:41], off
	v_add_u32_e32 v40, 0x2000, v34
	v_ashrrev_i32_e32 v41, 31, v40
	v_lshlrev_b64 v[40:41], 1, v[40:41]
	v_lshl_add_u64 v[42:43], v[32:33], 0, v[40:41]
	v_add_u32_e32 v34, 0x3000, v34
	global_load_dwordx4 v[142:145], v[42:43], off
	v_ashrrev_i32_e32 v35, 31, v34
	v_lshlrev_b64 v[42:43], 1, v[34:35]
	v_lshl_add_u64 v[32:33], v[32:33], 0, v[42:43]
	global_load_dwordx4 v[32:35], v[32:33], off
	s_waitcnt vmcnt(3)
	ds_write_b128 v91, v[44:47] offset:34816
	v_mul_lo_u32 v44, v56, s1
	v_add_lshl_u32 v56, v135, v44, 1
	v_add_u32_e32 v44, 0, v56
	s_waitcnt vmcnt(2)
	ds_write_b128 v44, v[138:141] offset:34816
	v_mul_lo_u32 v44, v54, s1
	v_add_lshl_u32 v54, v136, v44, 1
	v_add_u32_e32 v44, 0, v54
	s_waitcnt vmcnt(1)
	ds_write_b128 v44, v[142:145] offset:34816
	v_mul_lo_u32 v44, v52, s1
	v_add_lshl_u32 v52, v133, v44, 1
	v_add_u32_e32 v44, 0, v52
	s_waitcnt vmcnt(0)
	ds_write_b128 v44, v[32:35] offset:34816
	v_lshl_add_u64 v[32:33], s[16:17], 0, v[176:177]
	v_lshl_add_u64 v[34:35], v[32:33], 0, v[36:37]
	global_load_dwordx4 v[44:47], v[34:35], off
	v_lshl_add_u64 v[34:35], v[32:33], 0, v[38:39]
	global_load_dwordx4 v[36:39], v[34:35], off
	v_lshl_add_u64 v[34:35], v[32:33], 0, v[40:41]
	global_load_dwordx4 v[134:137], v[34:35], off
	v_lshl_add_u64 v[32:33], v[32:33], 0, v[42:43]
	global_load_dwordx4 v[32:35], v[32:33], off
	v_add_u32_e32 v40, s82, v58
	s_waitcnt vmcnt(3)
	ds_write_b128 v40, v[44:47]
	v_add_u32_e32 v40, s82, v56
	s_waitcnt vmcnt(2)
	ds_write_b128 v40, v[36:39]
	v_add_u32_e32 v36, s82, v54
	s_waitcnt vmcnt(1)
	ds_write_b128 v36, v[134:137]
	v_add_u32_e32 v36, s82, v52
	s_waitcnt vmcnt(0)
	ds_write_b128 v36, v[32:35]
	s_waitcnt lgkmcnt(0)
	s_barrier
; #define LAS __attribute__((address_space(3)))
; DI void mma16(f32x4 (&acc)[8], const LAS unsigned char* At, int arow0, const LAS unsigned char* Bt, int lane) {
;     const int l15 = lane & 15, quad = lane >> 4;
; #pragma unroll
;     for (int ks = 0; ks < 4; ++ks) {
;         const bf16x8 a = *(const LAS bf16x8*)(At + sw(arow0 + l15, 32 * ks + 8 * quad) * 2);
; #pragma unroll
;         for (int cg = 0; cg < 8; ++cg) { const bf16x8 b = *(const LAS bf16x8*)(Bt + sw(16 * cg + l15, 32 * ks + 8 * quad) * 2);
;             acc[cg] = __builtin_amdgcn_mfma_f32_16x16x32_bf16(a, b, acc[cg], 0, 0, 0); }
;     }
; }
; DI void out_unit(const Inputs& in, int l, unsigned char* ws, int half, int u, LAS unsigned char* lds, int tid) {
;     ...
;     zero8(F); mma16(F, Qt, 16 * wave, Kt, lane);
; #pragma unroll
;     for (int r = 0; r < 4; ++r) { const int i = 16 * wave + 4 * quad + r; const float qwf = __expf((float)(i + 1) * lgf);
; #pragma unroll
;         for (int cg = 0; cg < 8; ++cg) O[cg][r] += qwf * F[cg][r]; }
;     zero8(F); mma16(F, Qt, 16 * wave, VTt, lane);
	ds_read_b128 v[32:35], v53
	ds_read_b128 v[36:39], v55 offset:34816
	s_waitcnt lgkmcnt(0)
	v_mfma_f32_16x16x32_bf16 v[40:43], v[32:35], v[36:39], 0
	ds_read_b128 v[36:39], v57 offset:34816
	s_waitcnt lgkmcnt(0)
	v_mfma_f32_16x16x32_bf16 v[44:47], v[32:35], v[36:39], 0
	ds_read_b128 v[36:39], v59 offset:34816
	s_waitcnt lgkmcnt(0)
	v_mfma_f32_16x16x32_bf16 v[52:55], v[32:35], v[36:39], 0
	ds_read_b128 v[36:39], v61 offset:34816
	s_waitcnt lgkmcnt(0)
	v_mfma_f32_16x16x32_bf16 v[56:59], v[32:35], v[36:39], 0
	ds_read_b128 v[36:39], v62 offset:34816
	s_waitcnt lgkmcnt(0)
	v_mfma_f32_16x16x32_bf16 v[134:137], v[32:35], v[36:39], 0
	ds_read_b128 v[36:39], v63 offset:34816
	s_waitcnt lgkmcnt(0)
	v_mfma_f32_16x16x32_bf16 v[138:141], v[32:35], v[36:39], 0
	ds_read_b128 v[36:39], v70 offset:34816
	s_waitcnt lgkmcnt(0)
	v_mfma_f32_16x16x32_bf16 v[142:145], v[32:35], v[36:39], 0
	ds_read_b128 v[36:39], v71 offset:34816
	s_waitcnt lgkmcnt(0)
	v_mfma_f32_16x16x32_bf16 v[146:149], v[32:35], v[36:39], 0
	ds_read_b128 v[36:39], v72
	ds_read_b128 v[70:73], v73 offset:34816
	s_waitcnt lgkmcnt(0)
	v_mfma_f32_16x16x32_bf16 v[70:73], v[36:39], v[70:73], v[40:43]
	s_nop 2
	ds_read_b128 v[40:43], v74 offset:34816
	s_waitcnt lgkmcnt(0)
	v_mfma_f32_16x16x32_bf16 v[44:47], v[36:39], v[40:43], v[44:47]
	ds_read_b128 v[40:43], v75 offset:34816
	s_waitcnt lgkmcnt(0)
	v_mfma_f32_16x16x32_bf16 v[52:55], v[36:39], v[40:43], v[52:55]
	ds_read_b128 v[40:43], v76 offset:34816
	s_waitcnt lgkmcnt(0)
	v_mfma_f32_16x16x32_bf16 v[56:59], v[36:39], v[40:43], v[56:59]
	ds_read_b128 v[40:43], v77 offset:34816
	s_waitcnt lgkmcnt(0)
	v_mfma_f32_16x16x32_bf16 v[74:77], v[36:39], v[40:43], v[134:137]
	ds_read_b128 v[40:43], v78 offset:34816
	s_waitcnt lgkmcnt(0)
	v_mfma_f32_16x16x32_bf16 v[134:137], v[36:39], v[40:43], v[138:141]
	ds_read_b128 v[40:43], v79 offset:34816
	s_waitcnt lgkmcnt(0)
	v_mfma_f32_16x16x32_bf16 v[138:141], v[36:39], v[40:43], v[142:145]
	ds_read_b128 v[40:43], v80 offset:34816
	s_waitcnt lgkmcnt(0)
	v_mfma_f32_16x16x32_bf16 v[142:145], v[36:39], v[40:43], v[146:149]
	ds_read_b128 v[40:43], v81
	ds_read_b128 v[78:81], v82 offset:34816
	s_waitcnt lgkmcnt(0)
	v_mfma_f32_16x16x32_bf16 v[70:73], v[40:43], v[78:81], v[70:73]
	ds_read_b128 v[78:81], v83 offset:34816
	s_waitcnt lgkmcnt(0)
	v_mfma_f32_16x16x32_bf16 v[78:81], v[40:43], v[78:81], v[44:47]
	s_nop 2
	ds_read_b128 v[44:47], v84 offset:34816
	s_waitcnt lgkmcnt(0)
	v_mfma_f32_16x16x32_bf16 v[52:55], v[40:43], v[44:47], v[52:55]
	ds_read_b128 v[44:47], v85 offset:34816
	s_waitcnt lgkmcnt(0)
	v_mfma_f32_16x16x32_bf16 v[56:59], v[40:43], v[44:47], v[56:59]
	ds_read_b128 v[44:47], v86 offset:34816
	s_waitcnt lgkmcnt(0)
	v_mfma_f32_16x16x32_bf16 v[74:77], v[40:43], v[44:47], v[74:77]
	ds_read_b128 v[44:47], v87 offset:34816
	s_waitcnt lgkmcnt(0)
	v_mfma_f32_16x16x32_bf16 v[82:85], v[40:43], v[44:47], v[134:137]
	ds_read_b128 v[44:47], v88 offset:34816
	s_waitcnt lgkmcnt(0)
	v_mfma_f32_16x16x32_bf16 v[134:137], v[40:43], v[44:47], v[138:141]
	ds_read_b128 v[44:47], v89 offset:34816
	s_waitcnt lgkmcnt(0)
	v_mfma_f32_16x16x32_bf16 v[86:89], v[40:43], v[44:47], v[142:145]
	ds_read_b128 v[44:47], v90
	ds_read_b128 v[138:141], v92 offset:34816
	ds_read_b128 v[90:93], v93 offset:34816
	s_waitcnt lgkmcnt(0)
	v_mfma_f32_16x16x32_bf16 v[78:81], v[44:47], v[90:93], v[78:81]
	ds_read_b128 v[90:93], v94 offset:34816
	s_waitcnt lgkmcnt(0)
	v_mfma_f32_16x16x32_bf16 v[52:55], v[44:47], v[90:93], v[52:55]
	ds_read_b128 v[90:93], v95 offset:34816
	s_waitcnt lgkmcnt(0)
	v_mfma_f32_16x16x32_bf16 v[56:59], v[44:47], v[90:93], v[56:59]
	ds_read_b128 v[90:93], v96 offset:34816
	s_waitcnt lgkmcnt(0)
	v_mfma_f32_16x16x32_bf16 v[74:77], v[44:47], v[90:93], v[74:77]
	ds_read_b128 v[90:93], v97 offset:34816
	ds_read_b128 v[94:97], v99 offset:34816
	s_nop 2
	v_fma_f32 v12, v48, v56, v12
	s_waitcnt lgkmcnt(1)
	v_mfma_f32_16x16x32_bf16 v[82:85], v[44:47], v[90:93], v[82:85]
	ds_read_b128 v[90:93], v98 offset:34816
	v_fma_f32 v16, v48, v74, v16
	v_mfma_f32_16x16x32_bf16 v[70:73], v[44:47], v[138:141], v[70:73]
	s_nop 4
	v_fma_f32 v20, v48, v82, v20
	s_waitcnt lgkmcnt(1)
	v_mfma_f32_16x16x32_bf16 v[86:89], v[44:47], v[94:97], v[86:89]
	v_fma_f32 v96, v48, v52, v8
	v_fma_f32 v94, v48, v70, v0
	v_cvt_f32_i32_e32 v0, v102
	s_waitcnt lgkmcnt(0)
	v_mfma_f32_16x16x32_bf16 v[90:93], v[44:47], v[90:93], v[134:137]
	v_fma_f32 v95, v48, v78, v4
	s_nop 1
	v_fma_f32 v28, v48, v86, v28
	v_mul_f32_e32 v0, v0, v60
	v_mul_f32_e32 v0, 0xbfb8aa3b, v0
	v_exp_f32_e32 v0, v0
	s_nop 0
	v_fma_f32 v24, v48, v90, v24
	v_fma_f32 v90, v0, v71, v1
	v_fma_f32 v97, v0, v79, v5
	v_fma_f32 v98, v0, v53, v9
	v_fma_f32 v13, v0, v57, v13
	v_fma_f32 v17, v0, v75, v17
	v_fma_f32 v21, v0, v83, v21
	v_fma_f32 v25, v0, v91, v25
	v_fma_f32 v29, v0, v87, v29
	v_cvt_f32_i32_e32 v0, v100
	v_mul_f32_e32 v0, v0, v60
	v_mul_f32_e32 v0, 0xbfb8aa3b, v0
	v_exp_f32_e32 v0, v0
	s_nop 0
	v_fma_f32 v8, v0, v80, v6
	v_fma_f32 v6, v0, v54, v10
	v_add_u32_e32 v10, 4, v101
	v_cvt_f32_i32_e32 v10, v10
	v_fma_f32 v9, v0, v72, v2
	v_fma_f32 v5, v0, v58, v14
	v_fma_f32 v4, v0, v76, v18
	v_mul_f32_e32 v10, v10, v60
	v_mul_f32_e32 v10, 0xbfb8aa3b, v10
	v_exp_f32_e32 v10, v10
	v_fma_f32 v2, v0, v84, v22
	v_fma_f32 v1, v0, v92, v26
	v_fma_f32 v0, v0, v88, v30
	v_fmac_f32_e32 v11, v10, v55
	ds_read_b128 v[52:55], v114
	v_fmac_f32_e32 v7, v10, v81
	v_fmac_f32_e32 v23, v10, v85
	v_fmac_f32_e32 v31, v10, v89
	ds_read_b128 v[78:81], v104
	ds_read_b128 v[82:85], v50
	ds_read_b128 v[86:89], v49
	ds_read_b128 v[48:51], v51
	v_fmac_f32_e32 v15, v10, v59
	s_waitcnt lgkmcnt(4)
; #define LAS __attribute__((address_space(3)))
; DI void out_unit(const Inputs& in, int l, unsigned char* ws, int half, int u, LAS unsigned char* lds, int tid) {
;     ...
;     zero8(F); mma16(F, Qt, 16 * wave, VTt, lane);
;     LAS bf16_t* Pn = (LAS bf16_t*)Ps;
; #pragma unroll
;     for (int r = 0; r < 4; ++r) { const int i = 16 * wave + 4 * quad + r; const float qwb = __expf((float)(128 - i) * lgb);
;         float sm = 0.f;
; #pragma unroll
;         for (int cg = 0; cg < 8; ++cg) { O[cg][r] += qwb * F[cg][r]; sm += O[cg][r]; }
;         sm += __shfl_xor(sm, 1); sm += __shfl_xor(sm, 2); sm += __shfl_xor(sm, 4); sm += __shfl_xor(sm, 8);
;         const float mean = sm * (1.f / 128.f); float vs = 0.f;
; #pragma unroll
;         for (int cg = 0; cg < 8; ++cg) { const float dd = O[cg][r] - mean; vs += dd * dd; }
;         vs += __shfl_xor(vs, 1); vs += __shfl_xor(vs, 2); vs += __shfl_xor(vs, 4); vs += __shfl_xor(vs, 8);
;         const float rinv = __builtin_amdgcn_rsqf(vs * (1.f / 128.f) + EPS);
	v_mfma_f32_16x16x32_bf16 v[52:55], v[32:35], v[52:55], 0
	ds_read_b128 v[56:59], v112
	ds_read_b128 v[60:63], v110
	v_fmac_f32_e32 v19, v10, v77
	ds_read_b128 v[74:77], v106
	s_waitcnt lgkmcnt(3)
	v_mfma_f32_16x16x32_bf16 v[48:51], v[36:39], v[48:51], v[52:55]
	v_fmac_f32_e32 v3, v10, v73
	ds_read_b128 v[70:73], v108
	v_sub_u32_e32 v14, 0x80, v101
	ds_read_b128 v[52:55], v105
	s_waitcnt lgkmcnt(4)
	v_mfma_f32_16x16x32_bf16 v[56:59], v[32:35], v[56:59], 0
	v_cvt_f32_i32_e32 v14, v14
	v_fmac_f32_e32 v27, v10, v93
	v_lshlrev_b32_e32 v10, 1, v68
	s_waitcnt lgkmcnt(0)
	v_mfma_f32_16x16x32_bf16 v[52:55], v[36:39], v[52:55], v[56:59]
	v_mul_f32_e32 v14, v14, v67
	v_mul_f32_e32 v14, 0xbfb8aa3b, v14
	v_exp_f32_e32 v14, v14
	ds_read_b128 v[56:59], v107
	v_mfma_f32_16x16x32_bf16 v[60:63], v[32:35], v[60:63], 0
	v_add3_u32 v10, v65, v10, v103
	s_waitcnt lgkmcnt(0)
	v_mfma_f32_16x16x32_bf16 v[56:59], v[36:39], v[56:59], v[60:63]
	v_mfma_f32_16x16x32_bf16 v[70:73], v[32:35], v[70:73], 0
	s_nop 3
	ds_read_b128 v[60:63], v109
	s_waitcnt lgkmcnt(0)
	v_mfma_f32_16x16x32_bf16 v[60:63], v[36:39], v[60:63], v[70:73]
	s_nop 2
	ds_read_b128 v[70:73], v111
	v_mfma_f32_16x16x32_bf16 v[74:77], v[32:35], v[74:77], 0
	s_waitcnt lgkmcnt(0)
	v_mfma_f32_16x16x32_bf16 v[70:73], v[36:39], v[70:73], v[74:77]
	v_mfma_f32_16x16x32_bf16 v[78:81], v[32:35], v[78:81], 0
	s_nop 4
	ds_read_b128 v[74:77], v113
	s_waitcnt lgkmcnt(0)
	v_mfma_f32_16x16x32_bf16 v[74:77], v[36:39], v[74:77], v[78:81]
	s_nop 2
	ds_read_b128 v[78:81], v115
	v_mfma_f32_16x16x32_bf16 v[82:85], v[32:35], v[82:85], 0
	s_waitcnt lgkmcnt(0)
	v_mfma_f32_16x16x32_bf16 v[78:81], v[36:39], v[78:81], v[82:85]
	v_mfma_f32_16x16x32_bf16 v[32:35], v[32:35], v[86:89], 0
	s_nop 4
	ds_read_b128 v[82:85], v116
	s_waitcnt lgkmcnt(0)
	v_mfma_f32_16x16x32_bf16 v[32:35], v[36:39], v[82:85], v[32:35]
	ds_read_b128 v[36:39], v117
	s_waitcnt lgkmcnt(0)
	v_mfma_f32_16x16x32_bf16 v[36:39], v[40:43], v[36:39], v[48:51]
	s_nop 2
	ds_read_b128 v[48:51], v118
	s_waitcnt lgkmcnt(0)
	v_mfma_f32_16x16x32_bf16 v[48:51], v[40:43], v[48:51], v[52:55]
	s_nop 2
	ds_read_b128 v[52:55], v119
	s_waitcnt lgkmcnt(0)
	v_mfma_f32_16x16x32_bf16 v[52:55], v[40:43], v[52:55], v[56:59]
	s_nop 2
	ds_read_b128 v[56:59], v120
	s_waitcnt lgkmcnt(0)
	v_mfma_f32_16x16x32_bf16 v[56:59], v[40:43], v[56:59], v[60:63]
	s_nop 2
	ds_read_b128 v[60:63], v121
	s_waitcnt lgkmcnt(0)
	v_mfma_f32_16x16x32_bf16 v[60:63], v[40:43], v[60:63], v[70:73]
	s_nop 2
	ds_read_b128 v[70:73], v122
	s_waitcnt lgkmcnt(0)
	v_mfma_f32_16x16x32_bf16 v[70:73], v[40:43], v[70:73], v[74:77]
	s_nop 2
	ds_read_b128 v[74:77], v123
	s_waitcnt lgkmcnt(0)
	v_mfma_f32_16x16x32_bf16 v[74:77], v[40:43], v[74:77], v[78:81]
	s_nop 2
	ds_read_b128 v[78:81], v124
	s_waitcnt lgkmcnt(0)
	v_mfma_f32_16x16x32_bf16 v[78:81], v[40:43], v[78:81], v[32:35]
	s_nop 2
	ds_read_b128 v[32:35], v125
	ds_read_b128 v[40:43], v127
	s_waitcnt lgkmcnt(1)
	v_mfma_f32_16x16x32_bf16 v[32:35], v[44:47], v[32:35], v[36:39]
	s_nop 2
	ds_read_b128 v[36:39], v126
	s_waitcnt lgkmcnt(1)
	v_mfma_f32_16x16x32_bf16 v[40:43], v[44:47], v[40:43], v[52:55]
	s_nop 1
	v_fmac_f32_e32 v94, v14, v32
	v_add_f32_e32 v18, 0, v94
	ds_read_b128 v[52:55], v129
	s_waitcnt lgkmcnt(1)
	v_mfma_f32_16x16x32_bf16 v[36:39], v[44:47], v[36:39], v[48:51]
	s_nop 0
	v_fmac_f32_e32 v96, v14, v40
	s_nop 0
	ds_read_b128 v[48:51], v128
	s_waitcnt lgkmcnt(1)
	v_mfma_f32_16x16x32_bf16 v[52:55], v[44:47], v[52:55], v[60:63]
	s_nop 1
	v_fmac_f32_e32 v95, v14, v36
	v_add_f32_e32 v18, v18, v95
	v_add_f32_e32 v18, v18, v96
	ds_read_b128 v[60:63], v131
	s_waitcnt lgkmcnt(1)
	v_mfma_f32_16x16x32_bf16 v[48:51], v[44:47], v[48:51], v[56:59]
	v_fmac_f32_e32 v16, v14, v52
	s_nop 1
	ds_read_b128 v[56:59], v130
	s_waitcnt lgkmcnt(0)
	v_mfma_f32_16x16x32_bf16 v[56:59], v[44:47], v[56:59], v[70:73]
	s_nop 2
	ds_read_b128 v[70:73], v132
	v_fmac_f32_e32 v12, v14, v48
	v_add_f32_e32 v18, v18, v12
	v_mfma_f32_16x16x32_bf16 v[60:63], v[44:47], v[60:63], v[74:77]
	v_add_f32_e32 v18, v18, v16
	v_fmac_f32_e32 v20, v14, v56
	v_add_f32_e32 v18, v18, v20
	s_waitcnt lgkmcnt(0)
	v_mfma_f32_16x16x32_bf16 v[44:47], v[44:47], v[70:73], v[78:81]
	s_nop 2
	v_fmac_f32_e32 v24, v14, v60
	v_add_f32_e32 v18, v18, v24
	s_nop 2
	v_fmac_f32_e32 v28, v14, v44
	v_add_f32_e32 v14, v18, v28
	ds_bpermute_b32 v18, v206, v14
	s_waitcnt lgkmcnt(0)
	v_add_f32_e32 v14, v14, v18
	ds_bpermute_b32 v18, v207, v14
	s_waitcnt lgkmcnt(0)
	v_add_f32_e32 v14, v14, v18
	ds_bpermute_b32 v18, v208, v14
	s_waitcnt lgkmcnt(0)
	v_add_f32_e32 v14, v14, v18
	ds_bpermute_b32 v18, v209, v14
	s_waitcnt lgkmcnt(0)
	v_add_f32_e32 v14, v14, v18
	v_fmac_f32_e32 v95, 0xbc000000, v14
	v_fmac_f32_e32 v94, 0xbc000000, v14
	v_mul_f32_e32 v18, v95, v95
	v_fmac_f32_e32 v18, v94, v94
	v_fmac_f32_e32 v96, 0xbc000000, v14
	v_fmac_f32_e32 v18, v96, v96
	v_fmac_f32_e32 v12, 0xbc000000, v14
	v_fmac_f32_e32 v18, v12, v12
	v_fmac_f32_e32 v16, 0xbc000000, v14
	v_fmac_f32_e32 v18, v16, v16
	v_fmac_f32_e32 v20, 0xbc000000, v14
	v_fmac_f32_e32 v18, v20, v20
	v_fmac_f32_e32 v24, 0xbc000000, v14
	v_fmac_f32_e32 v18, v24, v24
	v_fmac_f32_e32 v28, 0xbc000000, v14
	v_fmac_f32_e32 v18, v28, v28
	ds_bpermute_b32 v14, v206, v18
	s_waitcnt lgkmcnt(0)
	v_add_f32_e32 v14, v18, v14
	ds_bpermute_b32 v18, v207, v14
	s_waitcnt lgkmcnt(0)
	v_add_f32_e32 v14, v14, v18
	ds_bpermute_b32 v18, v208, v14
	s_waitcnt lgkmcnt(0)
	v_add_f32_e32 v14, v14, v18
	ds_bpermute_b32 v18, v209, v14
	s_waitcnt lgkmcnt(0)
; DI void out_unit(const Inputs& in, int l, unsigned char* ws, int half, int u, LAS unsigned char* lds, int tid) {
;     ...
;     for (int r = 0; r < 4; ++r) { const int i = 16 * wave + 4 * quad + r; const float qwb = __expf((float)(128 - i) * lgb);
;         float sm = 0.f;
; #pragma unroll
;         for (int cg = 0; cg < 8; ++cg) { O[cg][r] += qwb * F[cg][r]; sm += O[cg][r]; }
;         sm += __shfl_xor(sm, 1); sm += __shfl_xor(sm, 2); sm += __shfl_xor(sm, 4); sm += __shfl_xor(sm, 8);
;         const float mean = sm * (1.f / 128.f); float vs = 0.f;
; #pragma unroll
;         for (int cg = 0; cg < 8; ++cg) { const float dd = O[cg][r] - mean; vs += dd * dd; }
;         vs += __shfl_xor(vs, 1); vs += __shfl_xor(vs, 2); vs += __shfl_xor(vs, 4); vs += __shfl_xor(vs, 8);
;         const float rinv = __builtin_amdgcn_rsqf(vs * (1.f / 128.f) + EPS);
; #pragma unroll
;         for (int cg = 0; cg < 8; ++cg) Pn[(4 * quad + r) * TS + 16 * cg + l15] = f2bf((O[cg][r] - mean) * rinv);
;     }
	v_add_f32_e32 v14, v14, v18
	v_fmamk_f32 v14, v14, 0x3c000000, v217
	v_rsq_f32_e32 v14, v14
	s_nop 0
	v_mul_f32_e32 v12, v12, v14
	v_cvt_pk_bf16_f32 v12, v12, s0
	ds_write_b16 v10, v12 offset:96
	v_mul_f32_e32 v12, v16, v14
	v_cvt_pk_bf16_f32 v12, v12, s0
	ds_write_b16 v10, v12 offset:128
	v_mul_f32_e32 v12, v20, v14
	v_cvt_pk_bf16_f32 v12, v12, s0
	ds_write_b16 v10, v12 offset:160
	v_mul_f32_e32 v12, v24, v14
	v_cvt_pk_bf16_f32 v12, v12, s0
	ds_write_b16 v10, v12 offset:192
	v_mul_f32_e32 v12, v28, v14
	v_cvt_pk_bf16_f32 v12, v12, s0
	ds_write_b16 v10, v12 offset:224
	v_sub_u32_e32 v12, 0x7f, v101
	v_cvt_f32_i32_e32 v12, v12
	v_mul_f32_e32 v18, v94, v14
	v_cvt_pk_bf16_f32 v18, v18, s0
	ds_write_b16 v10, v18
	v_mul_f32_e32 v12, v12, v67
	v_mul_f32_e32 v12, 0xbfb8aa3b, v12
	v_exp_f32_e32 v12, v12
	v_mul_f32_e32 v18, v95, v14
	v_cvt_pk_bf16_f32 v18, v18, s0
	ds_write_b16 v10, v18 offset:32
	v_fmac_f32_e32 v90, v12, v33
	v_mul_f32_e32 v18, v96, v14
	v_add_f32_e32 v14, 0, v90
	v_fmac_f32_e32 v97, v12, v37
	v_add_f32_e32 v14, v14, v97
	v_fmac_f32_e32 v98, v12, v41
	v_add_f32_e32 v14, v14, v98
	v_fmac_f32_e32 v13, v12, v49
	v_add_f32_e32 v14, v14, v13
	v_fmac_f32_e32 v17, v12, v53
	v_add_f32_e32 v14, v14, v17
	v_fmac_f32_e32 v21, v12, v57
	v_add_f32_e32 v14, v14, v21
	v_fmac_f32_e32 v25, v12, v61
	v_add_f32_e32 v14, v14, v25
	v_fmac_f32_e32 v29, v12, v45
	v_add_f32_e32 v12, v14, v29
	ds_bpermute_b32 v14, v206, v12
	v_cvt_pk_bf16_f32 v18, v18, s0
	ds_write_b16 v10, v18 offset:64
	s_waitcnt lgkmcnt(1)
	v_add_f32_e32 v12, v12, v14
	ds_bpermute_b32 v14, v207, v12
	s_waitcnt lgkmcnt(0)
	v_add_f32_e32 v12, v12, v14
	ds_bpermute_b32 v14, v208, v12
	s_waitcnt lgkmcnt(0)
	v_add_f32_e32 v12, v12, v14
	ds_bpermute_b32 v14, v209, v12
	s_waitcnt lgkmcnt(0)
	v_add_f32_e32 v12, v12, v14
	v_fmac_f32_e32 v97, 0xbc000000, v12
	v_fmac_f32_e32 v90, 0xbc000000, v12
	v_mul_f32_e32 v14, v97, v97
	v_fmac_f32_e32 v14, v90, v90
	v_fmac_f32_e32 v98, 0xbc000000, v12
	v_fmac_f32_e32 v14, v98, v98
	v_fmac_f32_e32 v13, 0xbc000000, v12
	v_fmac_f32_e32 v14, v13, v13
	v_fmac_f32_e32 v17, 0xbc000000, v12
	v_fmac_f32_e32 v14, v17, v17
	v_fmac_f32_e32 v21, 0xbc000000, v12
	v_fmac_f32_e32 v14, v21, v21
	v_fmac_f32_e32 v25, 0xbc000000, v12
	v_fmac_f32_e32 v14, v25, v25
	v_fmac_f32_e32 v29, 0xbc000000, v12
	v_fmac_f32_e32 v14, v29, v29
	ds_bpermute_b32 v12, v206, v14
	s_waitcnt lgkmcnt(0)
	v_add_f32_e32 v12, v14, v12
	ds_bpermute_b32 v14, v207, v12
	s_waitcnt lgkmcnt(0)
	v_add_f32_e32 v12, v12, v14
	ds_bpermute_b32 v14, v208, v12
	s_waitcnt lgkmcnt(0)
	v_add_f32_e32 v12, v12, v14
	ds_bpermute_b32 v14, v209, v12
	s_waitcnt lgkmcnt(0)
	v_add_f32_e32 v12, v12, v14
	v_fmamk_f32 v12, v12, 0x3c000000, v217
	v_rsq_f32_e32 v12, v12
	s_nop 0
	v_mul_f32_e32 v13, v13, v12
	v_cvt_pk_bf16_f32 v13, v13, s0
	v_mul_f32_e32 v14, v90, v12
	ds_write_b16 v10, v13 offset:368
	v_mul_f32_e32 v13, v17, v12
	v_cvt_pk_bf16_f32 v14, v14, s0
	v_cvt_pk_bf16_f32 v13, v13, s0
	ds_write_b16 v10, v14 offset:272
	v_mul_f32_e32 v14, v97, v12
	ds_write_b16 v10, v13 offset:400
	v_mul_f32_e32 v13, v21, v12
	v_cvt_pk_bf16_f32 v14, v14, s0
	v_cvt_pk_bf16_f32 v13, v13, s0
	ds_write_b16 v10, v14 offset:304
	v_mul_f32_e32 v14, v98, v12
	ds_write_b16 v10, v13 offset:432
	v_mul_f32_e32 v13, v25, v12
	v_mul_f32_e32 v12, v29, v12
	v_cvt_pk_bf16_f32 v12, v12, s0
	ds_write_b16 v10, v12 offset:496
	v_sub_u32_e32 v12, 0x80, v102
	v_cvt_f32_i32_e32 v12, v12
	v_cvt_pk_bf16_f32 v13, v13, s0
	ds_write_b16 v10, v13 offset:464
	v_cvt_pk_bf16_f32 v14, v14, s0
	v_mul_f32_e32 v12, v12, v67
	v_mul_f32_e32 v12, 0xbfb8aa3b, v12
	v_exp_f32_e32 v12, v12
	ds_write_b16 v10, v14 offset:336
	v_fmac_f32_e32 v9, v12, v34
	v_add_f32_e32 v13, 0, v9
	v_fmac_f32_e32 v8, v12, v38
	v_add_f32_e32 v13, v13, v8
	v_fmac_f32_e32 v6, v12, v42
	v_add_f32_e32 v13, v13, v6
	v_fmac_f32_e32 v5, v12, v50
	v_add_f32_e32 v13, v13, v5
	v_fmac_f32_e32 v4, v12, v54
	v_add_f32_e32 v13, v13, v4
	v_fmac_f32_e32 v2, v12, v58
	v_add_f32_e32 v13, v13, v2
	v_fmac_f32_e32 v1, v12, v62
	v_add_f32_e32 v13, v13, v1
	v_fmac_f32_e32 v0, v12, v46
	v_add_f32_e32 v12, v13, v0
	ds_bpermute_b32 v13, v206, v12
	s_waitcnt lgkmcnt(0)
	v_add_f32_e32 v12, v12, v13
	ds_bpermute_b32 v13, v207, v12
	s_waitcnt lgkmcnt(0)
	v_add_f32_e32 v12, v12, v13
	ds_bpermute_b32 v13, v208, v12
	s_waitcnt lgkmcnt(0)
	v_add_f32_e32 v12, v12, v13
	ds_bpermute_b32 v13, v209, v12
	s_waitcnt lgkmcnt(0)
	v_add_f32_e32 v12, v12, v13
	v_fmac_f32_e32 v8, 0xbc000000, v12
	v_fmac_f32_e32 v9, 0xbc000000, v12
	v_mul_f32_e32 v13, v8, v8
	v_fmac_f32_e32 v13, v9, v9
	v_fmac_f32_e32 v6, 0xbc000000, v12
	v_fmac_f32_e32 v13, v6, v6
	v_fmac_f32_e32 v5, 0xbc000000, v12
	v_fmac_f32_e32 v13, v5, v5
	v_fmac_f32_e32 v4, 0xbc000000, v12
	v_fmac_f32_e32 v13, v4, v4
	v_fmac_f32_e32 v2, 0xbc000000, v12
	v_fmac_f32_e32 v13, v2, v2
	v_fmac_f32_e32 v1, 0xbc000000, v12
	v_fmac_f32_e32 v13, v1, v1
	v_fmac_f32_e32 v0, 0xbc000000, v12
	v_fmac_f32_e32 v13, v0, v0
	ds_bpermute_b32 v12, v206, v13
	s_waitcnt lgkmcnt(0)
	v_add_f32_e32 v12, v13, v12
	ds_bpermute_b32 v13, v207, v12
	s_waitcnt lgkmcnt(0)
	v_add_f32_e32 v12, v12, v13
	ds_bpermute_b32 v13, v208, v12
	s_waitcnt lgkmcnt(0)
	v_add_f32_e32 v12, v12, v13
	ds_bpermute_b32 v13, v209, v12
	s_waitcnt lgkmcnt(0)
; #define LAS __attribute__((address_space(3)))
; DI unsigned cvt_pk_bf16(float lo, float hi) { const f32x2 v = {lo, hi}; return __builtin_bit_cast(unsigned, __builtin_convertvector(v, bf16x2_t)); }
; DI float sigmoidf_(float x) { return __builtin_amdgcn_rcpf(1.f + __builtin_amdgcn_exp2f(-1.4426950408889634f * x)); }
; #define LDS_WAIT() asm volatile("s_waitcnt lgkmcnt(0)" ::: "memory")
; DI void unpack8(const u32x4 w, float (&f)[8]) { f[0] = bflo(w.x); f[1] = bfhi(w.x); f[2] = bflo(w.y); f[3] = bfhi(w.y); f[4] = bflo(w.z); f[5] = bfhi(w.z); f[6] = bflo(w.w); f[7] = bfhi(w.w); }
; DI void out_unit(const Inputs& in, int l, unsigned char* ws, int half, int u, LAS unsigned char* lds, int tid) {
;     ...
;     for (int r = 0; r < 4; ++r) { const int i = 16 * wave + 4 * quad + r; const float qwb = __expf((float)(128 - i) * lgb);
;         float sm = 0.f;
; #pragma unroll
;         for (int cg = 0; cg < 8; ++cg) { O[cg][r] += qwb * F[cg][r]; sm += O[cg][r]; }
;         sm += __shfl_xor(sm, 1); sm += __shfl_xor(sm, 2); sm += __shfl_xor(sm, 4); sm += __shfl_xor(sm, 8);
;         const float mean = sm * (1.f / 128.f); float vs = 0.f;
; #pragma unroll
;         for (int cg = 0; cg < 8; ++cg) { const float dd = O[cg][r] - mean; vs += dd * dd; }
;         vs += __shfl_xor(vs, 1); vs += __shfl_xor(vs, 2); vs += __shfl_xor(vs, 4); vs += __shfl_xor(vs, 8);
;         const float rinv = __builtin_amdgcn_rsqf(vs * (1.f / 128.f) + EPS);
; #pragma unroll
;         for (int cg = 0; cg < 8; ++cg) Pn[(4 * quad + r) * TS + 16 * cg + l15] = f2bf((O[cg][r] - mean) * rinv);
;     }
;     LDS_WAIT();
;     { const int rr = lane >> 2, part = lane & 3; bf16_t* rowp = proj + (size_t)(row0 + 16 * wave + rr) * PC + 128 * h + 32 * part;
;       u32x4 gv[4];
; #pragma unroll
;       for (int q = 0; q < 4; ++q) gv[q] = *(const u32x4*)(rowp + C_RG + 8 * q);
; #pragma unroll
;       for (int q = 0; q < 4; ++q) { float g[8], o[8]; unpack8(gv[q], g); unpack8(*(const LAS u32x4*)(Pn + rr * TS + 32 * part + 8 * q), o);
; #pragma unroll
;           for (int e = 0; e < 8; ++e) o[e] = g[e] * sigmoidf_(g[e]) * o[e];
;           u32x4 w; w.x = cvt_pk_bf16(o[0], o[1]); w.y = cvt_pk_bf16(o[2], o[3]); w.z = cvt_pk_bf16(o[4], o[5]); w.w = cvt_pk_bf16(o[6], o[7]);
;           *(u32x4*)(rowp + C_RQ + 8 * q) = w; } }
	v_add_f32_e32 v12, v12, v13
	v_fmamk_f32 v12, v12, 0x3c000000, v217
	v_rsq_f32_e32 v12, v12
	s_nop 0
	v_mul_f32_e32 v0, v0, v12
	v_cvt_pk_bf16_f32 v0, v0, s0
	ds_write_b16 v10, v0 offset:768
	v_sub_u32_e32 v0, 0x80, v100
	v_cvt_f32_i32_e32 v0, v0
	v_mul_f32_e32 v1, v1, v12
	v_cvt_pk_bf16_f32 v1, v1, s0
	ds_write_b16 v10, v1 offset:736
	v_mul_f32_e32 v0, v0, v67
	v_mul_f32_e32 v0, 0xbfb8aa3b, v0
	v_exp_f32_e32 v0, v0
	v_mul_f32_e32 v9, v9, v12
	v_mul_f32_e32 v8, v8, v12
	v_mul_f32_e32 v6, v6, v12
	v_fmac_f32_e32 v3, v0, v35
	v_add_f32_e32 v1, 0, v3
	v_fmac_f32_e32 v7, v0, v39
	v_add_f32_e32 v1, v1, v7
	v_fmac_f32_e32 v11, v0, v43
	v_add_f32_e32 v1, v1, v11
	v_fmac_f32_e32 v15, v0, v51
	v_add_f32_e32 v1, v1, v15
	v_fmac_f32_e32 v19, v0, v55
	v_add_f32_e32 v1, v1, v19
	v_fmac_f32_e32 v23, v0, v59
	v_add_f32_e32 v1, v1, v23
	v_fmac_f32_e32 v27, v0, v63
	v_add_f32_e32 v1, v1, v27
	v_fmac_f32_e32 v31, v0, v47
	v_add_f32_e32 v0, v1, v31
	ds_bpermute_b32 v1, v206, v0
	v_mul_f32_e32 v5, v5, v12
	v_mul_f32_e32 v4, v4, v12
	v_mul_f32_e32 v2, v2, v12
	v_cvt_pk_bf16_f32 v9, v9, s0
	s_waitcnt lgkmcnt(0)
	v_add_f32_e32 v0, v0, v1
	ds_bpermute_b32 v1, v207, v0
	v_cvt_pk_bf16_f32 v8, v8, s0
	v_cvt_pk_bf16_f32 v6, v6, s0
	v_cvt_pk_bf16_f32 v5, v5, s0
	v_cvt_pk_bf16_f32 v4, v4, s0
	s_waitcnt lgkmcnt(0)
	v_add_f32_e32 v0, v0, v1
	ds_bpermute_b32 v1, v208, v0
	v_cvt_pk_bf16_f32 v2, v2, s0
	ds_write_b16 v10, v9 offset:544
	ds_write_b16 v10, v8 offset:576
	ds_write_b16 v10, v6 offset:608
	s_waitcnt lgkmcnt(3)
	v_add_f32_e32 v0, v0, v1
	ds_bpermute_b32 v1, v209, v0
	ds_write_b16 v10, v5 offset:640
	ds_write_b16 v10, v4 offset:672
	ds_write_b16 v10, v2 offset:704
	v_lshlrev_b32_e32 v2, 6, v66
	s_waitcnt lgkmcnt(3)
	v_add_f32_e32 v0, v0, v1
	v_fmac_f32_e32 v7, 0xbc000000, v0
	v_fmac_f32_e32 v3, 0xbc000000, v0
	v_mul_f32_e32 v1, v7, v7
	v_fmac_f32_e32 v1, v3, v3
	v_fmac_f32_e32 v11, 0xbc000000, v0
	v_fmac_f32_e32 v1, v11, v11
	v_fmac_f32_e32 v15, 0xbc000000, v0
	v_fmac_f32_e32 v1, v15, v15
	v_fmac_f32_e32 v19, 0xbc000000, v0
	v_fmac_f32_e32 v1, v19, v19
	v_fmac_f32_e32 v23, 0xbc000000, v0
	v_fmac_f32_e32 v1, v23, v23
	v_fmac_f32_e32 v27, 0xbc000000, v0
	v_fmac_f32_e32 v1, v27, v27
	v_fmac_f32_e32 v31, 0xbc000000, v0
	v_fmac_f32_e32 v1, v31, v31
	ds_bpermute_b32 v0, v206, v1
	v_and_b32_e32 v176, 0xc0, v2
	s_waitcnt lgkmcnt(0)
	v_add_f32_e32 v0, v1, v0
	ds_bpermute_b32 v1, v207, v0
	s_waitcnt lgkmcnt(0)
	v_add_f32_e32 v0, v0, v1
	ds_bpermute_b32 v1, v208, v0
	s_waitcnt lgkmcnt(0)
	v_add_f32_e32 v0, v0, v1
	ds_bpermute_b32 v1, v209, v0
	s_waitcnt lgkmcnt(0)
	v_add_f32_e32 v0, v0, v1
	v_fmamk_f32 v0, v0, 0x3c000000, v217
	v_rsq_f32_e32 v0, v0
	s_nop 0
	v_mul_f32_e32 v1, v3, v0
	v_cvt_pk_bf16_f32 v1, v1, s0
	ds_write_b16 v10, v1 offset:816
	v_mul_f32_e32 v1, v7, v0
	v_cvt_pk_bf16_f32 v1, v1, s0
	ds_write_b16 v10, v1 offset:848
	v_mul_f32_e32 v1, v11, v0
	v_cvt_pk_bf16_f32 v1, v1, s0
	ds_write_b16 v10, v1 offset:880
	v_mul_f32_e32 v1, v15, v0
	v_cvt_pk_bf16_f32 v1, v1, s0
	ds_write_b16 v10, v1 offset:912
	v_mul_f32_e32 v1, v19, v0
	v_cvt_pk_bf16_f32 v1, v1, s0
	ds_write_b16 v10, v1 offset:944
	v_mul_f32_e32 v1, v23, v0
	v_cvt_pk_bf16_f32 v1, v1, s0
	ds_write_b16 v10, v1 offset:976
	v_mul_f32_e32 v1, v27, v0
	v_mul_f32_e32 v0, v31, v0
	v_cvt_pk_bf16_f32 v1, v1, s0
	v_cvt_pk_bf16_f32 v0, v0, s0
	ds_write_b16 v10, v1 offset:1008
	ds_write_b16 v10, v0 offset:1040
	v_bfe_u32 v10, v66, 2, 4
	v_add_u32_e32 v0, s14, v69
	v_or_b32_e32 v0, v0, v10
	v_ashrrev_i32_e32 v1, 31, v0
	v_lshlrev_b64 v[0:1], 14, v[0:1]
	v_lshl_add_u64 v[0:1], s[6:7], 0, v[0:1]
	v_lshl_add_u64 v[0:1], v[0:1], 0, s[44:45]
	v_lshl_add_u64 v[8:9], v[0:1], 0, v[176:177]
	s_mov_b64 s[14:15], 0x1800
	v_add_co_u32_e32 v0, vcc, s30, v8
	s_waitcnt lgkmcnt(0)
	v_lshl_add_u64 v[16:17], v[8:9], 0, s[14:15]
	s_nop 0
	v_addc_co_u32_e32 v1, vcc, 0, v9, vcc
	global_load_dwordx4 v[12:15], v[0:1], off offset:2048
	s_nop 0
	global_load_dwordx4 v[0:3], v[16:17], off offset:48
	global_load_dwordx4 v[4:7], v[16:17], off offset:32
	s_nop 0
	global_load_dwordx4 v[16:19], v[16:17], off offset:16
	v_mul_u32_u24_e32 v10, 0x110, v10
	v_add3_u32 v10, v65, v10, v176
	ds_read_b128 v[20:23], v10
	ds_read_b128 v[24:27], v10 offset:16
	ds_read_b128 v[28:31], v10 offset:32
	ds_read_b128 v[32:35], v10 offset:48
	s_waitcnt lgkmcnt(3)
	v_lshlrev_b32_e32 v36, 16, v20
	v_and_b32_e32 v37, 0xffff0000, v20
	v_lshlrev_b32_e32 v20, 16, v21
	v_and_b32_e32 v21, 0xffff0000, v21
	s_waitcnt vmcnt(3)
	v_lshlrev_b32_e32 v10, 16, v12
	v_and_b32_e32 v11, 0xffff0000, v12
	v_mul_f32_e32 v12, 0xbfb8aa3b, v10
	v_exp_f32_e32 v12, v12
	s_nop 0
	v_add_f32_e32 v12, 1.0, v12
	v_rcp_f32_e32 v38, v12
	v_mul_f32_e32 v12, 0xbfb8aa3b, v11
	v_exp_f32_e32 v12, v12
	s_nop 0
	v_add_f32_e32 v12, 1.0, v12
	v_rcp_f32_e32 v39, v12
	v_lshlrev_b32_e32 v12, 16, v13
	v_and_b32_e32 v13, 0xffff0000, v13
	v_pk_mul_f32 v[10:11], v[38:39], v[10:11]
	s_nop 0
	v_pk_mul_f32 v[10:11], v[10:11], v[36:37]
	v_mul_f32_e32 v36, 0xbfb8aa3b, v12
	v_mul_f32_e32 v37, 0xbfb8aa3b, v13
	v_exp_f32_e32 v36, v36
	v_exp_f32_e32 v37, v37
	v_cvt_pk_bf16_f32 v10, v10, v11
	v_add_f32_e32 v36, 1.0, v36
	v_add_f32_e32 v37, 1.0, v37
	v_rcp_f32_e32 v36, v36
	v_rcp_f32_e32 v37, v37
	s_nop 0
	v_pk_mul_f32 v[12:13], v[36:37], v[12:13]
	s_nop 0
	v_pk_mul_f32 v[12:13], v[12:13], v[20:21]
	v_lshlrev_b32_e32 v20, 16, v14
	v_and_b32_e32 v21, 0xffff0000, v14
	v_mul_f32_e32 v14, 0xbfb8aa3b, v20
	v_exp_f32_e32 v14, v14
	v_lshlrev_b32_e32 v36, 16, v22
	v_and_b32_e32 v37, 0xffff0000, v22
	v_lshlrev_b32_e32 v22, 16, v23
	v_add_f32_e32 v14, 1.0, v14
	v_rcp_f32_e32 v38, v14
	v_mul_f32_e32 v14, 0xbfb8aa3b, v21
	v_exp_f32_e32 v14, v14
	v_and_b32_e32 v23, 0xffff0000, v23
	v_cvt_pk_bf16_f32 v11, v12, v13
	v_add_f32_e32 v14, 1.0, v14
	v_rcp_f32_e32 v39, v14
	v_lshlrev_b32_e32 v14, 16, v15
	v_and_b32_e32 v15, 0xffff0000, v15
	v_pk_mul_f32 v[20:21], v[38:39], v[20:21]
	s_nop 0
	v_pk_mul_f32 v[20:21], v[20:21], v[36:37]
	v_mul_f32_e32 v36, 0xbfb8aa3b, v14
	v_mul_f32_e32 v37, 0xbfb8aa3b, v15
	v_exp_f32_e32 v36, v36
	v_exp_f32_e32 v37, v37
	v_cvt_pk_bf16_f32 v12, v20, v21
	v_add_f32_e32 v36, 1.0, v36
	v_add_f32_e32 v37, 1.0, v37
	v_rcp_f32_e32 v36, v36
	v_rcp_f32_e32 v37, v37
	s_nop 0
	v_pk_mul_f32 v[14:15], v[36:37], v[14:15]
	s_nop 0
	v_pk_mul_f32 v[14:15], v[14:15], v[22:23]
	s_nop 0
	v_cvt_pk_bf16_f32 v13, v14, v15
	global_store_dwordx4 v[8:9], v[10:13], off offset:3072
	s_waitcnt vmcnt(1)
; #define LAS __attribute__((address_space(3)))
; DI unsigned cvt_pk_bf16(float lo, float hi) { const f32x2 v = {lo, hi}; return __builtin_bit_cast(unsigned, __builtin_convertvector(v, bf16x2_t)); }
; DI float sigmoidf_(float x) { return __builtin_amdgcn_rcpf(1.f + __builtin_amdgcn_exp2f(-1.4426950408889634f * x)); }
; DI void unpack8(const u32x4 w, float (&f)[8]) { f[0] = bflo(w.x); f[1] = bfhi(w.x); f[2] = bflo(w.y); f[3] = bfhi(w.y); f[4] = bflo(w.z); f[5] = bfhi(w.z); f[6] = bflo(w.w); f[7] = bfhi(w.w); }
; DI void out_unit(const Inputs& in, int l, unsigned char* ws, int half, int u, LAS unsigned char* lds, int tid) {
;     ...
;       for (int q = 0; q < 4; ++q) gv[q] = *(const u32x4*)(rowp + C_RG + 8 * q);
; #pragma unroll
;       for (int q = 0; q < 4; ++q) { float g[8], o[8]; unpack8(gv[q], g); unpack8(*(const LAS u32x4*)(Pn + rr * TS + 32 * part + 8 * q), o);
; #pragma unroll
;           for (int e = 0; e < 8; ++e) o[e] = g[e] * sigmoidf_(g[e]) * o[e];
;           u32x4 w; w.x = cvt_pk_bf16(o[0], o[1]); w.y = cvt_pk_bf16(o[2], o[3]); w.z = cvt_pk_bf16(o[4], o[5]); w.w = cvt_pk_bf16(o[6], o[7]);
;           *(u32x4*)(rowp + C_RQ + 8 * q) = w; } }
;     __syncthreads();
	s_nop 0
	v_lshlrev_b32_e32 v10, 16, v16
	v_and_b32_e32 v11, 0xffff0000, v16
	v_mul_f32_e32 v14, 0xbfb8aa3b, v10
	v_mul_f32_e32 v15, 0xbfb8aa3b, v11
	v_exp_f32_e32 v14, v14
	v_exp_f32_e32 v15, v15
	s_waitcnt lgkmcnt(2)
	v_lshlrev_b32_e32 v12, 16, v24
	v_and_b32_e32 v13, 0xffff0000, v24
	v_add_f32_e32 v14, 1.0, v14
	v_add_f32_e32 v15, 1.0, v15
	v_rcp_f32_e32 v14, v14
	v_rcp_f32_e32 v15, v15
	s_nop 0
	v_pk_mul_f32 v[10:11], v[14:15], v[10:11]
	s_nop 0
	v_pk_mul_f32 v[10:11], v[10:11], v[12:13]
	v_lshlrev_b32_e32 v12, 16, v17
	v_and_b32_e32 v13, 0xffff0000, v17
	v_mul_f32_e32 v16, 0xbfb8aa3b, v12
	v_mul_f32_e32 v17, 0xbfb8aa3b, v13
	v_exp_f32_e32 v16, v16
	v_exp_f32_e32 v17, v17
	v_lshlrev_b32_e32 v14, 16, v25
	v_and_b32_e32 v15, 0xffff0000, v25
	v_add_f32_e32 v16, 1.0, v16
	v_add_f32_e32 v17, 1.0, v17
	v_rcp_f32_e32 v16, v16
	v_rcp_f32_e32 v17, v17
	v_cvt_pk_bf16_f32 v10, v10, v11
	v_pk_mul_f32 v[12:13], v[16:17], v[12:13]
	s_nop 0
	v_pk_mul_f32 v[12:13], v[12:13], v[14:15]
	v_lshlrev_b32_e32 v14, 16, v18
	v_and_b32_e32 v15, 0xffff0000, v18
	v_mul_f32_e32 v18, 0xbfb8aa3b, v14
	v_exp_f32_e32 v18, v18
	v_lshlrev_b32_e32 v16, 16, v26
	v_and_b32_e32 v17, 0xffff0000, v26
	v_cvt_pk_bf16_f32 v11, v12, v13
	v_add_f32_e32 v18, 1.0, v18
	v_rcp_f32_e32 v20, v18
	v_mul_f32_e32 v18, 0xbfb8aa3b, v15
	v_exp_f32_e32 v18, v18
	s_nop 0
	v_add_f32_e32 v18, 1.0, v18
	v_rcp_f32_e32 v21, v18
	v_lshlrev_b32_e32 v18, 16, v27
	v_pk_mul_f32 v[14:15], v[20:21], v[14:15]
	s_nop 0
	v_pk_mul_f32 v[14:15], v[14:15], v[16:17]
	v_lshlrev_b32_e32 v16, 16, v19
	v_and_b32_e32 v17, 0xffff0000, v19
	v_mul_f32_e32 v20, 0xbfb8aa3b, v16
	v_mul_f32_e32 v21, 0xbfb8aa3b, v17
	v_exp_f32_e32 v20, v20
	v_exp_f32_e32 v21, v21
	v_and_b32_e32 v19, 0xffff0000, v27
	v_cvt_pk_bf16_f32 v12, v14, v15
	v_add_f32_e32 v20, 1.0, v20
	v_add_f32_e32 v21, 1.0, v21
	v_rcp_f32_e32 v20, v20
	v_rcp_f32_e32 v21, v21
	s_nop 0
	v_pk_mul_f32 v[16:17], v[20:21], v[16:17]
	s_nop 0
	v_pk_mul_f32 v[16:17], v[16:17], v[18:19]
	s_nop 0
	v_cvt_pk_bf16_f32 v13, v16, v17
	global_store_dwordx4 v[8:9], v[10:13], off offset:3088
	s_nop 1
	v_lshlrev_b32_e32 v10, 16, v4
	v_and_b32_e32 v11, 0xffff0000, v4
	v_mul_f32_e32 v4, 0xbfb8aa3b, v10
	v_exp_f32_e32 v4, v4
	s_waitcnt lgkmcnt(1)
	v_lshlrev_b32_e32 v12, 16, v28
	v_and_b32_e32 v13, 0xffff0000, v28
	v_add_f32_e32 v4, 1.0, v4
	v_rcp_f32_e32 v14, v4
	v_mul_f32_e32 v4, 0xbfb8aa3b, v11
	v_exp_f32_e32 v4, v4
	s_nop 0
	v_add_f32_e32 v4, 1.0, v4
	v_rcp_f32_e32 v15, v4
	v_lshlrev_b32_e32 v4, 16, v5
	v_and_b32_e32 v5, 0xffff0000, v5
	v_pk_mul_f32 v[10:11], v[14:15], v[10:11]
	v_mul_f32_e32 v14, 0xbfb8aa3b, v4
	v_mul_f32_e32 v15, 0xbfb8aa3b, v5
	v_exp_f32_e32 v14, v14
	v_exp_f32_e32 v15, v15
	v_pk_mul_f32 v[10:11], v[10:11], v[12:13]
	v_lshlrev_b32_e32 v12, 16, v29
	v_add_f32_e32 v14, 1.0, v14
	v_add_f32_e32 v15, 1.0, v15
	v_rcp_f32_e32 v14, v14
	v_rcp_f32_e32 v15, v15
	v_and_b32_e32 v13, 0xffff0000, v29
	v_pk_mul_f32 v[4:5], v[14:15], v[4:5]
	s_nop 0
	v_pk_mul_f32 v[12:13], v[4:5], v[12:13]
	v_lshlrev_b32_e32 v4, 16, v6
	v_and_b32_e32 v5, 0xffff0000, v6
	v_mul_f32_e32 v6, 0xbfb8aa3b, v4
	v_exp_f32_e32 v6, v6
	v_lshlrev_b32_e32 v14, 16, v30
	v_and_b32_e32 v15, 0xffff0000, v30
	v_add_f32_e32 v6, 1.0, v6
	v_rcp_f32_e32 v16, v6
	v_mul_f32_e32 v6, 0xbfb8aa3b, v5
	v_exp_f32_e32 v6, v6
	s_nop 0
	v_add_f32_e32 v6, 1.0, v6
	v_rcp_f32_e32 v17, v6
	v_lshlrev_b32_e32 v6, 16, v31
	v_pk_mul_f32 v[4:5], v[16:17], v[4:5]
	s_nop 0
	v_pk_mul_f32 v[14:15], v[4:5], v[14:15]
	v_lshlrev_b32_e32 v4, 16, v7
	v_and_b32_e32 v5, 0xffff0000, v7
	v_mul_f32_e32 v16, 0xbfb8aa3b, v4
	v_mul_f32_e32 v17, 0xbfb8aa3b, v5
	v_exp_f32_e32 v16, v16
	v_exp_f32_e32 v17, v17
	v_and_b32_e32 v7, 0xffff0000, v31
	v_add_f32_e32 v16, 1.0, v16
	v_add_f32_e32 v17, 1.0, v17
	v_rcp_f32_e32 v16, v16
	v_rcp_f32_e32 v17, v17
	s_nop 0
	v_pk_mul_f32 v[4:5], v[16:17], v[4:5]
	s_nop 0
	v_pk_mul_f32 v[16:17], v[4:5], v[6:7]
	v_cvt_pk_bf16_f32 v4, v10, v11
	v_cvt_pk_bf16_f32 v5, v12, v13
	v_cvt_pk_bf16_f32 v6, v14, v15
	v_cvt_pk_bf16_f32 v7, v16, v17
	global_store_dwordx4 v[8:9], v[4:7], off offset:3104
	s_nop 1
	v_lshlrev_b32_e32 v4, 16, v0
	v_and_b32_e32 v5, 0xffff0000, v0
	v_mul_f32_e32 v0, 0xbfb8aa3b, v4
	v_exp_f32_e32 v0, v0
	s_waitcnt lgkmcnt(0)
	v_lshlrev_b32_e32 v6, 16, v32
	v_and_b32_e32 v7, 0xffff0000, v32
	v_add_f32_e32 v0, 1.0, v0
	v_rcp_f32_e32 v10, v0
	v_mul_f32_e32 v0, 0xbfb8aa3b, v5
	v_exp_f32_e32 v0, v0
	s_nop 0
	v_add_f32_e32 v0, 1.0, v0
	v_rcp_f32_e32 v11, v0
	v_lshlrev_b32_e32 v0, 16, v1
	v_and_b32_e32 v1, 0xffff0000, v1
	v_pk_mul_f32 v[4:5], v[10:11], v[4:5]
	v_mul_f32_e32 v10, 0xbfb8aa3b, v0
	v_mul_f32_e32 v11, 0xbfb8aa3b, v1
	v_exp_f32_e32 v10, v10
	v_exp_f32_e32 v11, v11
	v_pk_mul_f32 v[4:5], v[4:5], v[6:7]
	v_lshlrev_b32_e32 v6, 16, v33
	v_add_f32_e32 v10, 1.0, v10
	v_add_f32_e32 v11, 1.0, v11
	v_rcp_f32_e32 v10, v10
	v_rcp_f32_e32 v11, v11
	v_and_b32_e32 v7, 0xffff0000, v33
	v_pk_mul_f32 v[0:1], v[10:11], v[0:1]
	s_nop 0
	v_pk_mul_f32 v[6:7], v[0:1], v[6:7]
	v_lshlrev_b32_e32 v0, 16, v2
	v_and_b32_e32 v1, 0xffff0000, v2
	v_mul_f32_e32 v2, 0xbfb8aa3b, v0
	v_exp_f32_e32 v2, v2
	v_lshlrev_b32_e32 v10, 16, v34
	v_and_b32_e32 v11, 0xffff0000, v34
	v_add_f32_e32 v2, 1.0, v2
	v_rcp_f32_e32 v12, v2
	v_mul_f32_e32 v2, 0xbfb8aa3b, v1
	v_exp_f32_e32 v2, v2
	s_nop 0
	v_add_f32_e32 v2, 1.0, v2
	v_rcp_f32_e32 v13, v2
	v_lshlrev_b32_e32 v2, 16, v35
	v_pk_mul_f32 v[0:1], v[12:13], v[0:1]
	s_nop 0
	v_pk_mul_f32 v[10:11], v[0:1], v[10:11]
	v_lshlrev_b32_e32 v0, 16, v3
	v_and_b32_e32 v1, 0xffff0000, v3
	v_mul_f32_e32 v12, 0xbfb8aa3b, v0
	v_mul_f32_e32 v13, 0xbfb8aa3b, v1
	v_exp_f32_e32 v12, v12
	v_exp_f32_e32 v13, v13
	v_and_b32_e32 v3, 0xffff0000, v35
	v_add_f32_e32 v12, 1.0, v12
	v_add_f32_e32 v13, 1.0, v13
	v_rcp_f32_e32 v12, v12
	v_rcp_f32_e32 v13, v13
	s_nop 0
	v_pk_mul_f32 v[0:1], v[12:13], v[0:1]
	s_nop 0
	v_pk_mul_f32 v[12:13], v[0:1], v[2:3]
	v_cvt_pk_bf16_f32 v0, v4, v5
	v_cvt_pk_bf16_f32 v1, v6, v7
	v_cvt_pk_bf16_f32 v2, v10, v11
	v_cvt_pk_bf16_f32 v3, v12, v13
	global_store_dwordx4 v[8:9], v[0:3], off offset:3120
	s_barrier
	s_cbranch_scc0 .LBB0_731
